# v11 plus P5 GLU GEMM as 128 tiles of 192 rows on WGs 128..255, each followed by one half context unit
# speedup vs baseline: 1.0092x; 1.0092x over previous
.LBB0_360:
	s_or_b64 exec, exec, s[6:7]
	s_add_u32 s60, s54, 0xb800000
	s_addc_u32 s61, s55, 0
	s_cmpk_gt_i32 s38, 0x7f
	s_waitcnt lgkmcnt(0)
	s_barrier
	s_cbranch_scc0 .LBB0_365
	s_cmpk_lt_u32 s38, 0x80
	s_mov_b64 s[14:15], 0
	s_cbranch_scc0 .LBB0_366
	s_and_b32 s0, s38, 3
	s_lshl_b32 s1, s0, 2
	v_readlane_b32 s16, v242, 0
	v_mov_b32_e32 v4, v0
	v_mov_b32_e32 v1, s1
	v_readlane_b32 s20, v242, 4
	v_readlane_b32 s21, v242, 5
	s_nop 4
	global_load_dword v2, v1, s[20:21]
	global_load_dword v5, v1, s[20:21] offset:16
	s_mov_b32 s7, 0xbfb8aa3b
	s_mov_b32 s8, 0x42ce8ed0
	s_mov_b32 s9, 0xc2b17218
	v_mov_b32_e32 v8, 0x7f800000
	s_mov_b32 s10, 0x3f2aaaab
	s_mov_b32 s6, 0x3f317218
	v_mov_b32_e32 v9, 0x3ecc95a3
	s_mov_b32 s4, 0x7f800000
	s_mov_b32 s5, 0x33800000
	v_mov_b32_e32 v10, 0x3f2aaada
	s_lshl_b32 s1, s38, 6
	s_add_i32 s1, s1, 0x7fffe000
	v_readfirstlane_b32 s11, v4
	s_and_b32 s3, s1, 0x7fffff00
	s_ashr_i32 s1, s11, 6
	v_and_b32_e32 v12, 15, v4
	s_lshl_b32 s16, s0, 8
	v_readlane_b32 s18, v242, 2
	v_mov_b32_e32 v3, 0
	s_movk_i32 s18, 0x1400
	v_readlane_b32 s17, v242, 1
	s_mov_b32 s17, 0
	v_bfe_u32 v13, v4, 4, 2
	v_and_b32_e32 v1, 63, v4
	v_readlane_b32 s19, v242, 3
	v_readlane_b32 s22, v242, 6
	v_readlane_b32 s23, v242, 7
	v_readlane_b32 s24, v242, 8
	v_readlane_b32 s25, v242, 9
	v_readlane_b32 s26, v242, 10
	s_movk_i32 s19, 0xffee
	s_movk_i32 s20, 0xffed
	s_movk_i32 s21, 0xffdf
	s_movk_i32 s22, 0xffde
	s_movk_i32 s23, 0xffdd
	s_movk_i32 s24, 0xffcf
	s_movk_i32 s25, 0xffce
	s_movk_i32 s26, 0xffcd
	v_mov_b32_e32 v34, v3
	v_mov_b32_e32 v35, v3
	v_mov_b32_e32 v36, v3
	v_mov_b32_e32 v37, v3
	v_mov_b32_e32 v38, v3
	v_mov_b32_e32 v39, v3
	v_mov_b32_e32 v40, v3
	v_mov_b32_e32 v41, v3
	v_mov_b32_e32 v50, v3
	v_mov_b32_e32 v51, v3
	v_mov_b32_e32 v52, v3
	v_mov_b32_e32 v53, v3
	v_mov_b32_e32 v66, v3
	v_mov_b32_e32 v67, v3
	v_mov_b32_e32 v68, v3
	v_mov_b32_e32 v69, v3
	v_mov_b32_e32 v25, v3
	v_mov_b32_e32 v26, v3
	v_mov_b32_e32 v27, v3
	v_mov_b32_e32 v28, v3
	v_mov_b32_e32 v29, v3
	v_mov_b32_e32 v30, v3
	v_mov_b32_e32 v31, v3
	v_mov_b32_e32 v32, v3
	v_mov_b32_e32 v33, v3
	v_mov_b32_e32 v62, v3
	v_mov_b32_e32 v63, v3
	v_mov_b32_e32 v64, v3
	v_mov_b32_e32 v65, v3
	v_mov_b32_e32 v70, v3
	v_mov_b32_e32 v71, v3
	v_mov_b32_e32 v72, v3
	v_mov_b32_e32 v73, v3
	v_mov_b32_e32 v74, v3
	v_mov_b32_e32 v75, v3
	v_mov_b32_e32 v76, v3
	v_mov_b32_e32 v77, v3
	v_mov_b32_e32 v94, v3
	v_mov_b32_e32 v95, v3
	v_mov_b32_e32 v96, v3
	s_waitcnt vmcnt(1)
	v_mul_f32_e32 v6, 0xbfb8aa3b, v2
	v_fma_f32 v11, v2, s7, -v6
	v_rndne_f32_e32 v14, v6
	v_fmac_f32_e32 v11, 0xb2a5705f, v2
	v_sub_f32_e32 v6, v6, v14
	v_add_f32_e32 v6, v6, v11
	v_cvt_i32_f32_e32 v14, v14
	v_exp_f32_e32 v6, v6
	s_waitcnt vmcnt(0)
	v_mul_f32_e32 v7, 0xbfb8aa3b, v5
	v_cmp_nlt_f32_e32 vcc, s8, v2
	v_fma_f32 v15, v5, s7, -v7
	v_ldexp_f32 v6, v6, v14
	v_rndne_f32_e32 v16, v7
	v_cndmask_b32_e32 v6, 0, v6, vcc
	v_cmp_ngt_f32_e32 vcc, s9, v2
	v_fmac_f32_e32 v15, 0xb2a5705f, v5
	v_sub_f32_e32 v7, v7, v16
	v_cndmask_b32_e32 v2, v8, v6, vcc
	v_add_f32_e32 v7, v7, v15
	v_add_f32_e32 v14, 1.0, v2
	v_cvt_i32_f32_e32 v11, v16
	v_exp_f32_e32 v15, v7
	v_add_f32_e32 v16, -1.0, v14
	v_frexp_mant_f32_e32 v17, v14
	v_cvt_f64_f32_e32 v[6:7], v14
	v_sub_f32_e32 v18, v16, v14
	v_frexp_exp_i32_f64_e32 v6, v[6:7]
	v_cmp_gt_f32_e32 vcc, s10, v17
	v_sub_f32_e32 v16, v2, v16
	v_add_f32_e32 v7, 1.0, v18
	v_subbrev_co_u32_e32 v6, vcc, 0, v6, vcc
	v_add_f32_e32 v7, v16, v7
	v_sub_u32_e32 v16, 0, v6
	v_cvt_f32_i32_e32 v6, v6
	v_ldexp_f32 v14, v14, v16
	v_ldexp_f32 v7, v7, v16
	v_add_f32_e32 v16, -1.0, v14
	v_add_f32_e32 v17, 1.0, v14
	v_add_f32_e32 v18, 1.0, v16
	v_add_f32_e32 v19, -1.0, v17
	v_sub_f32_e32 v18, v14, v18
	v_sub_f32_e32 v14, v14, v19
	v_mul_f32_e32 v19, 0x3f317218, v6
	v_add_f32_e32 v18, v7, v18
	v_add_f32_e32 v7, v7, v14
	v_fma_f32 v14, v6, s6, -v19
	v_add_f32_e32 v20, v16, v18
	v_add_f32_e32 v21, v17, v7
	v_fmac_f32_e32 v14, 0xb102e308, v6
	v_sub_f32_e32 v6, v16, v20
	v_sub_f32_e32 v16, v17, v21
	v_rcp_f32_e32 v17, v21
	v_add_f32_e32 v22, v19, v14
	v_add_f32_e32 v7, v7, v16
	v_sub_f32_e32 v16, v22, v19
	v_sub_f32_e32 v14, v14, v16
	v_mul_f32_e32 v16, v20, v17
	v_add_f32_e32 v6, v18, v6
	v_mul_f32_e32 v18, v21, v16
	v_fma_f32 v19, v16, v21, -v18
	v_fmac_f32_e32 v19, v16, v7
	v_add_f32_e32 v23, v18, v19
	v_sub_f32_e32 v24, v20, v23
	v_sub_f32_e32 v18, v23, v18
	v_sub_f32_e32 v20, v20, v24
	v_sub_f32_e32 v18, v18, v19
	v_sub_f32_e32 v19, v20, v23
	v_add_f32_e32 v6, v6, v19
	v_add_f32_e32 v6, v18, v6
	v_add_f32_e32 v18, v24, v6
	v_mul_f32_e32 v19, v17, v18
	v_sub_f32_e32 v20, v24, v18
	v_mul_f32_e32 v23, v21, v19
	v_add_f32_e32 v6, v6, v20
	v_add_f32_e32 v20, v16, v19
	v_fma_f32 v21, v19, v21, -v23
	v_sub_f32_e32 v16, v20, v16
	v_fmac_f32_e32 v21, v19, v7
	v_sub_f32_e32 v7, v19, v16
	v_add_f32_e32 v16, v23, v21
	v_sub_f32_e32 v19, v16, v23
	v_sub_f32_e32 v23, v18, v16
	v_sub_f32_e32 v18, v18, v23
	v_sub_f32_e32 v16, v18, v16
	v_sub_f32_e32 v19, v19, v21
	v_add_f32_e32 v6, v6, v16
	v_add_f32_e32 v6, v19, v6
	v_add_f32_e32 v6, v23, v6
	v_mul_f32_e32 v6, v17, v6
	v_add_f32_e32 v6, v7, v6
	v_add_f32_e32 v7, v20, v6
	v_mul_f32_e32 v16, v7, v7
	v_fmamk_f32 v19, v16, 0x3e9b6dac, v9
	v_sub_f32_e32 v17, v7, v20
	v_ldexp_f32 v18, v7, 1
	v_mul_f32_e32 v7, v7, v16
	v_fmaak_f32 v16, v16, v19, 0x3f2aaada
	v_mul_f32_e32 v7, v7, v16
	v_add_f32_e32 v16, v18, v7
	v_sub_f32_e32 v6, v6, v17
	v_sub_f32_e32 v17, v16, v18
	v_ldexp_f32 v6, v6, 1
	v_sub_f32_e32 v7, v7, v17
	v_add_f32_e32 v6, v6, v7
	v_add_f32_e32 v7, v16, v6
	v_sub_f32_e32 v16, v7, v16
	v_add_f32_e32 v17, v22, v7
	v_sub_f32_e32 v6, v6, v16
	v_sub_f32_e32 v16, v17, v22
	v_sub_f32_e32 v18, v17, v16
	v_sub_f32_e32 v7, v7, v16
	v_add_f32_e32 v16, v14, v6
	v_sub_f32_e32 v18, v22, v18
	v_sub_f32_e32 v19, v16, v14
	v_add_f32_e32 v7, v7, v18
	v_sub_f32_e32 v18, v16, v19
	v_sub_f32_e32 v6, v6, v19
	v_sub_f32_e32 v14, v14, v18
	v_add_f32_e32 v7, v16, v7
	v_add_f32_e32 v6, v6, v14
	v_add_f32_e32 v14, v17, v7
	v_sub_f32_e32 v16, v14, v17
	v_sub_f32_e32 v7, v7, v16
	v_add_f32_e32 v6, v6, v7
	v_add_f32_e32 v6, v14, v6
	v_cmp_neq_f32_e32 vcc, s4, v2
	v_mov_b32_e32 v21, v3
	v_mov_b32_e32 v22, v3
	v_cndmask_b32_e32 v6, v8, v6, vcc
	v_cmp_lt_f32_e64 vcc, |v2|, s5
	v_mov_b32_e32 v23, v3
	v_mov_b32_e32 v24, v3
	v_cndmask_b32_e32 v2, v6, v2, vcc
	v_mul_f32_e32 v140, 0xbfb8aa3b, v2
	v_ldexp_f32 v2, v15, v11
	v_cmp_nlt_f32_e32 vcc, s8, v5
	s_mul_i32 s8, s1, 0x1200
	v_exp_f32_e64 v145, -v140
	v_cndmask_b32_e32 v2, 0, v2, vcc
	v_cmp_ngt_f32_e32 vcc, s9, v5
	v_mov_b32_e32 v97, v3
	v_readlane_b32 s27, v242, 11
	v_cndmask_b32_e32 v2, v8, v2, vcc
	v_add_f32_e32 v5, 1.0, v2
	v_add_f32_e32 v6, -1.0, v5
	v_sub_f32_e32 v7, v6, v5
	v_add_f32_e32 v7, 1.0, v7
	v_sub_f32_e32 v6, v2, v6
	v_add_f32_e32 v11, v6, v7
	v_frexp_mant_f32_e32 v14, v5
	v_cvt_f64_f32_e32 v[6:7], v5
	v_frexp_exp_i32_f64_e32 v6, v[6:7]
	v_cmp_gt_f32_e32 vcc, s10, v14
	v_readlane_b32 s28, v242, 12
	v_readlane_b32 s29, v242, 13
	v_subbrev_co_u32_e32 v6, vcc, 0, v6, vcc
	v_sub_u32_e32 v7, 0, v6
	v_ldexp_f32 v5, v5, v7
	v_ldexp_f32 v7, v11, v7
	v_add_f32_e32 v11, -1.0, v5
	v_add_f32_e32 v16, 1.0, v5
	v_add_f32_e32 v14, 1.0, v11
	v_add_f32_e32 v17, -1.0, v16
	v_sub_f32_e32 v14, v5, v14
	v_sub_f32_e32 v5, v5, v17
	v_add_f32_e32 v5, v7, v5
	v_add_f32_e32 v14, v7, v14
	v_add_f32_e32 v7, v16, v5
	v_rcp_f32_e32 v17, v7
	v_add_f32_e32 v15, v11, v14
	v_sub_f32_e32 v11, v11, v15
	v_add_f32_e32 v11, v14, v11
	v_sub_f32_e32 v14, v16, v7
	v_add_f32_e32 v5, v5, v14
	v_mul_f32_e32 v14, v15, v17
	v_mul_f32_e32 v16, v7, v14
	v_fma_f32 v18, v14, v7, -v16
	v_fmac_f32_e32 v18, v14, v5
	v_add_f32_e32 v19, v16, v18
	v_sub_f32_e32 v20, v15, v19
	v_sub_f32_e32 v15, v15, v20
	v_sub_f32_e32 v16, v19, v16
	v_sub_f32_e32 v15, v15, v19
	v_add_f32_e32 v11, v11, v15
	v_sub_f32_e32 v15, v16, v18
	v_add_f32_e32 v11, v15, v11
	v_add_f32_e32 v15, v20, v11
	v_mul_f32_e32 v16, v17, v15
	v_mul_f32_e32 v18, v7, v16
	v_fma_f32 v7, v16, v7, -v18
	v_fmac_f32_e32 v7, v16, v5
	v_sub_f32_e32 v5, v20, v15
	v_add_f32_e32 v5, v11, v5
	v_add_f32_e32 v11, v18, v7
	v_sub_f32_e32 v19, v15, v11
	v_sub_f32_e32 v15, v15, v19
	v_sub_f32_e32 v18, v11, v18
	v_sub_f32_e32 v11, v15, v11
	v_add_f32_e32 v5, v5, v11
	v_sub_f32_e32 v7, v18, v7
	v_add_f32_e32 v5, v7, v5
	v_add_f32_e32 v7, v14, v16
	v_add_f32_e32 v5, v19, v5
	v_sub_f32_e32 v11, v7, v14
	v_mul_f32_e32 v5, v17, v5
	v_sub_f32_e32 v11, v16, v11
	v_add_f32_e32 v5, v11, v5
	v_cvt_f32_i32_e32 v6, v6
	v_add_f32_e32 v11, v7, v5
	v_mul_f32_e32 v14, v11, v11
	v_fmac_f32_e32 v9, 0x3e9b6dac, v14
	v_fmac_f32_e32 v10, v14, v9
	v_mul_f32_e32 v9, 0x3f317218, v6
	v_fma_f32 v15, v6, s6, -v9
	v_fmac_f32_e32 v15, 0xb102e308, v6
	v_sub_f32_e32 v6, v11, v7
	v_sub_f32_e32 v5, v5, v6
	v_add_f32_e32 v6, v9, v15
	v_sub_f32_e32 v7, v6, v9
	v_ldexp_f32 v9, v11, 1
	v_mul_f32_e32 v11, v11, v14
	v_mul_f32_e32 v10, v11, v10
	v_add_f32_e32 v11, v9, v10
	v_sub_f32_e32 v9, v11, v9
	v_ldexp_f32 v5, v5, 1
	v_sub_f32_e32 v9, v10, v9
	v_add_f32_e32 v5, v5, v9
	v_add_f32_e32 v9, v11, v5
	v_sub_f32_e32 v10, v9, v11
	v_sub_f32_e32 v5, v5, v10
	v_add_f32_e32 v10, v6, v9
	v_sub_f32_e32 v11, v10, v6
	v_sub_f32_e32 v14, v10, v11
	v_sub_f32_e32 v7, v15, v7
	v_sub_f32_e32 v6, v6, v14
	v_sub_f32_e32 v9, v9, v11
	v_add_f32_e32 v6, v9, v6
	v_add_f32_e32 v9, v7, v5
	v_sub_f32_e32 v11, v9, v7
	v_sub_f32_e32 v14, v9, v11
	v_sub_f32_e32 v7, v7, v14
	v_sub_f32_e32 v5, v5, v11
	v_add_f32_e32 v6, v9, v6
	v_add_f32_e32 v5, v5, v7
	v_add_f32_e32 v7, v10, v6
	v_sub_f32_e32 v9, v7, v10
	v_sub_f32_e32 v6, v6, v9
	v_add_f32_e32 v5, v5, v6
	v_add_f32_e32 v5, v7, v5
	v_cmp_neq_f32_e32 vcc, s4, v2
	s_lshl_b32 s4, s0, 7
	v_ashrrev_i32_e32 v15, 4, v4
	v_cndmask_b32_e32 v5, v8, v5, vcc
	v_cmp_lt_f32_e64 vcc, |v2|, s5
	s_lshl_b32 s5, s1, 5
	s_add_u32 s0, s68, s16
	v_cndmask_b32_e32 v2, v5, v2, vcc
	v_mul_f32_e32 v149, 0xbfb8aa3b, v2
	v_mul_f32_e32 v2, 0x80000000, v140
	v_exp_f32_e32 v147, v2
	v_mul_f32_e32 v2, 0, v149
	v_exp_f32_e32 v148, v2
	v_mul_f32_e32 v2, -2.0, v140
	v_exp_f32_e32 v143, v2
	v_add_f32_e32 v2, v149, v149
	v_exp_f32_e32 v144, v2
	v_mul_f32_e32 v2, 0xc0400000, v140
	v_exp_f32_e32 v142, v2
	v_mul_f32_e32 v2, 0x40400000, v149
	v_exp_f32_e32 v141, v2
	v_or_b32_e32 v2, s5, v12
	v_add_u32_e32 v5, s3, v2
	s_addc_u32 s1, s69, 0
	v_and_b32_e32 v2, 48, v4
	v_lshl_add_u64 v[6:7], s[0:1], 0, v[2:3]
	v_mad_i64_i32 v[8:9], s[6:7], v5, s18, v[6:7]
	v_or_b32_e32 v5, 16, v5
	v_mad_i64_i32 v[6:7], s[6:7], v5, s18, v[6:7]
	global_load_dwordx4 v[90:93], v[8:9], off
	global_load_dwordx4 v[86:89], v[8:9], off offset:64
	global_load_dwordx4 v[82:85], v[8:9], off offset:128
	global_load_dwordx4 v[78:81], v[8:9], off offset:192
	global_load_dwordx4 v[58:61], v[6:7], off
	global_load_dwordx4 v[54:57], v[6:7], off offset:64
	global_load_dwordx4 v[46:49], v[6:7], off offset:128
	global_load_dwordx4 v[42:45], v[6:7], off offset:192
	v_add_u32_e32 v16, s3, v15
	v_mov_b64_e32 v[6:7], s[68:69]
	v_mad_i64_i32 v[8:9], s[6:7], v16, s18, v[6:7]
	v_lshlrev_b32_e32 v10, 4, v4
	v_lshl_add_u64 v[8:9], v[8:9], 0, s[16:17]
	v_and_b32_e32 v10, 0xf0, v10
	v_mov_b32_e32 v11, v3
	v_lshl_add_u64 v[8:9], v[8:9], 0, v[10:11]
	global_load_dwordx4 v[98:101], v[8:9], off offset:1024
	global_load_dwordx4 v[102:105], v[8:9], off offset:2048
	v_add_u32_e32 v8, 0x200, v4
	v_ashrrev_i32_e32 v8, 4, v8
	v_add_u32_e32 v9, s3, v8
	v_mad_i64_i32 v[6:7], s[6:7], v9, s18, v[6:7]
	v_lshl_add_u64 v[6:7], v[6:7], 0, s[16:17]
	v_lshl_add_u64 v[6:7], v[6:7], 0, v[10:11]
	global_load_dwordx4 v[106:109], v[6:7], off offset:1024
	global_load_dwordx4 v[110:113], v[6:7], off offset:2048
	v_exp_f32_e32 v146, v149
	v_lshlrev_b32_e32 v14, 3, v13
	v_lshlrev_b32_e32 v5, 3, v4
	v_lshlrev_b32_e32 v13, 2, v13
	v_bfe_u32 v4, v4, 2, 2
	s_add_i32 s6, s8, 0
	v_add_u32_e32 v6, 0, v10
	v_add_u32_e32 v7, 0, v2
	v_sub_u32_e32 v17, v12, v13
	v_or_b32_e32 v4, v14, v4
	v_and_b32_e32 v5, 24, v5
	s_movk_i32 s8, 0x110
	v_add_u32_e32 v150, s5, v17
	v_add_u32_e32 v17, s6, v14
	v_add_u32_e32 v2, s6, v2
	v_add_u32_e32 v5, 0, v5
	v_mad_u64_u32 v[136:137], s[6:7], v15, s8, v[6:7]
	v_mad_u64_u32 v[134:135], s[6:7], v8, s8, v[6:7]
	v_mul_u32_u24_e32 v6, 0x110, v12
	v_mul_u32_u24_e32 v8, 0x90, v12
	v_mul_u32_u24_e32 v4, 0x110, v4
	v_lshl_add_u64 v[138:139], s[0:1], 0, v[10:11]
	v_sub_u32_e32 v10, v13, v12
	v_subrev_u32_e32 v153, s5, v10
	v_add_u32_e32 v154, 64, v9
	v_add_u32_e32 v155, 64, v16
	s_movk_i32 s16, 0xffef
	v_add_u32_e32 v152, v7, v6
	v_add_u32_e32 v151, v17, v8
	v_add_u32_e32 v137, v2, v8
	v_add_u32_e32 v135, v5, v4
	v_mov_b32_e32 v156, v150
	v_mov_b32_e32 v2, v3
	v_mov_b32_e32 v4, v3
	v_mov_b32_e32 v5, v3
	v_mov_b32_e32 v6, v3
	v_mov_b32_e32 v7, v3
	v_mov_b32_e32 v8, v3
	v_mov_b32_e32 v9, v3
	v_mov_b32_e32 v10, v3
	v_mov_b32_e32 v12, v3
	v_mov_b32_e32 v13, v3
	v_mov_b32_e32 v14, v3
	v_mov_b32_e32 v15, v3
	v_mov_b32_e32 v16, v3
	v_mov_b32_e32 v17, v3
	v_mov_b32_e32 v18, v3
	v_mov_b32_e32 v19, v3
	v_mov_b32_e32 v20, v3
	v_readlane_b32 s30, v242, 14
	v_readlane_b32 s31, v242, 15

.LBB0_378:
	s_add_i32 s3, s38, 0xffffff80
	s_cmpk_gt_i32 s38, 0x7f
	s_cselect_b32 s1, s3, 0x100000
	s_mov_b32 s98, s1
	v_mov_b32_e32 v13, v0
	v_readlane_b32 s94, v242, 40
	s_cmpk_gt_u32 s1, 0x7f
	v_readfirstlane_b32 s0, v13
	v_readlane_b32 s95, v242, 41
	s_cbranch_scc1 .LBB0_386
	v_lshlrev_b32_e32 v1, 4, v13
	v_add_u32_e32 v2, 0x2000, v1
	v_ashrrev_i32_e32 v3, 31, v2
	v_lshrrev_b32_e32 v3, 22, v3
	v_add_u32_e32 v3, v2, v3
	v_ashrrev_i32_e32 v10, 10, v3
	v_mul_i32_i24_e32 v3, 0x400, v10
	v_sub_u32_e32 v2, v2, v3
	v_lshrrev_b32_e32 v3, 4, v2
	v_bitop3_b32 v2, v3, v2, 32 bitop3:0x6c
	v_ashrrev_i32_e32 v3, 31, v2
	v_lshrrev_b32_e32 v3, 26, v3
	v_add_u32_e32 v3, v2, v3
	v_lshlrev_b32_e32 v4, 3, v10
	v_ashrrev_i32_e32 v11, 6, v3
	v_and_b32_e32 v4, -16, v4
	v_add_u32_e32 v4, v11, v4
	v_and_b32_e32 v5, 3, v11
	s_mov_b32 s4, 0x3fffe0
	v_lshrrev_b32_e32 v6, 2, v4
	v_lshlrev_b32_e32 v7, 1, v4
	v_and_b32_e32 v3, 0xc0, v3
	v_and_or_b32 v5, v4, s4, v5
	v_and_b32_e32 v6, 4, v6
	v_and_b32_e32 v7, 24, v7
	v_sub_u32_e32 v2, v2, v3
	v_mov_b32_e32 v3, 1
	v_or3_b32 v5, v5, v6, v7
	v_lshlrev_b32_e32 v6, 5, v10
	v_ashrrev_i16_sdwa v2, v3, sext(v2) dst_sel:DWORD dst_unused:UNUSED_PAD src0_sel:DWORD src1_sel:BYTE_0
	v_and_b32_e32 v6, 32, v6
	v_bfe_i32 v12, v2, 0, 16
	v_add_lshl_u32 v2, v6, v12, 1
	v_lshl_add_u32 v58, v5, 10, v2
	v_lshl_add_u32 v60, v4, 10, v2
	v_add_u32_e32 v60, 0xffffc000, v60
	v_bfe_i32 v2, v13, 27, 1
	v_lshrrev_b32_e32 v2, 22, v2
	v_add_u32_e32 v2, v1, v2
	v_and_b32_e32 v2, 0xfffffc00, v2
	v_sub_u32_e32 v1, v1, v2
	v_lshrrev_b32_e32 v2, 4, v1
	v_ashrrev_i32_e32 v4, 31, v13
	v_bitop3_b32 v1, v2, v1, 32 bitop3:0x6c
	v_lshrrev_b32_e32 v4, 26, v4
	v_ashrrev_i32_e32 v2, 31, v1
	v_add_u32_e32 v4, v13, v4
	v_lshrrev_b32_e32 v2, 26, v2
	v_ashrrev_i32_e32 v15, 6, v4
	v_add_u32_e32 v2, v1, v2
	v_lshlrev_b32_e32 v4, 3, v15
	v_ashrrev_i32_e32 v14, 6, v2
	v_and_b32_e32 v4, -16, v4
	v_add_u32_e32 v4, v14, v4
	v_and_b32_e32 v5, 3, v14
	v_and_or_b32 v5, v4, s4, v5
	s_and_b32 s4, s1, 7
	s_lshr_b32 s1, s1, 3
	s_mul_i32 s4, s4, 12
	s_add_i32 s4, s4, s1
	s_and_b32 s1, s4, 0xff
	s_mulk_i32 s1, 0xab
	s_lshr_b32 s1, s1, 11
	s_mul_i32 s5, s1, 6
	s_mul_i32 s1, s1, 12
	s_sub_i32 s1, s4, s1
	s_and_b32 s4, s1, 0xff
	s_add_i32 s1, s1, 0xfffa
	s_and_b32 s1, s1, 0xff
	s_min_u32 s1, s4, s1
	s_add_i32 s1, s1, s5
	s_ashr_i32 s14, s0, 6
	s_and_b32 s1, s1, 0xff
	s_ashr_i32 s15, s0, 8
	s_and_b32 s1, s98, 7
	s_lshl_b32 s1, s1, 3
	s_lshr_b32 s99, s98, 4
	s_add_i32 s1, s1, s99
	s_mul_i32 s99, s1, 0xc0
	s_lshl_b32 s100, s15, 4
	s_sub_i32 s99, s99, s100
	s_lshl_b32 s20, s14, 10
	s_mul_i32 s16, s1, 0x30000
	s_bitcmp1_b32 s98, 3
	v_lshrrev_b32_e32 v6, 2, v4
	v_lshlrev_b32_e32 v7, 1, v4
	v_and_b32_e32 v2, 0xc0, v2
	s_cselect_b64 s[6:7], -1, 0
	v_and_b32_e32 v6, 4, v6
	v_and_b32_e32 v7, 24, v7
	v_sub_u32_e32 v1, v1, v2
	s_and_b64 s[4:5], s[6:7], exec
	v_or3_b32 v5, v5, v6, v7
	v_lshlrev_b32_e32 v6, 5, v15
	v_ashrrev_i16_sdwa v1, v3, sext(v1) dst_sel:DWORD dst_unused:UNUSED_PAD src0_sel:DWORD src1_sel:BYTE_0
	s_cselect_b32 s18, 0x40000, 0
	v_and_b32_e32 v6, 32, v6
	v_bfe_i32 v16, v1, 0, 16
	s_add_u32 s8, s84, s18
	v_add_lshl_u32 v1, v6, v16, 1
	s_addc_u32 s9, s85, 0
	s_add_i32 s4, s20, 0
	v_lshl_add_u32 v62, v5, 10, v1
	s_add_i32 m0, s4, 0x10000
	v_lshl_add_u32 v64, v4, 10, v1
	global_load_lds_dwordx4 v62, s[8:9]
	s_add_i32 m0, s4, 0x12000
	s_add_u32 s10, s8, 0x20000
	global_load_lds_dwordx4 v58, s[8:9]
	s_addc_u32 s11, s9, 0
	s_add_i32 m0, s4, 0x14000
	v_mov_b32_e32 v63, 0
	global_load_lds_dwordx4 v62, s[10:11]
	s_add_i32 m0, s4, 0x16000
	v_mov_b32_e32 v59, v63
	global_load_lds_dwordx4 v58, s[10:11]
	s_add_u32 s10, s80, s16
	s_addc_u32 s11, s81, 0
	s_add_i32 s5, s4, 0x2000
	s_mov_b32 m0, s4
	s_add_u32 s22, s10, 0x18000
	global_load_lds_dwordx4 v64, s[10:11]
	s_mov_b32 m0, s5
	s_addc_u32 s23, s11, 0
	s_add_i32 s24, s4, 0x4000
	global_load_lds_dwordx4 v60, s[10:11]
	s_mov_b32 m0, s24
	s_add_i32 s25, s4, 0x6000
	global_load_lds_dwordx4 v64, s[22:23]
	s_mov_b32 m0, s25
	v_mov_b32_e32 v65, v63
	global_load_lds_dwordx4 v60, s[22:23]
	v_mov_b32_e32 v61, v63
	v_lshl_add_u64 v[8:9], s[8:9], 0, v[62:63]
	v_lshl_add_u64 v[6:7], s[8:9], 0, v[58:59]
	v_lshl_add_u64 v[4:5], s[10:11], 0, v[64:65]
	s_cmp_lg_u32 s15, 1
	v_lshl_add_u64 v[2:3], s[10:11], 0, v[60:61]
	s_cbranch_scc1 .LBB0_381
	s_barrier
.LBB0_381:
	v_lshrrev_b32_e32 v18, 1, v13
	v_and_b32_e32 v78, 24, v18
	s_lshl_b32 s14, s14, 5
	v_and_b32_e32 v17, 15, v13
	v_lshlrev_b32_e32 v18, 1, v78
	v_lshlrev_b32_e32 v13, 2, v13
	s_and_b32 s26, s14, 0x60
	v_lshl_or_b32 v1, s15, 6, v17
	v_lshl_or_b32 v17, v17, 6, v18
	s_lshl_b32 s15, s15, 13
	v_and_b32_e32 v13, 32, v13
	s_lshl_b32 s14, s26, 7
	v_bitop3_b32 v18, v17, s15, v13 bitop3:0xde
	v_bitop3_b32 v13, v17, s14, v13 bitop3:0xde
	s_mov_b64 s[14:15], 0x80
	s_add_i32 m0, s4, 0x18000
	v_lshl_add_u64 v[8:9], v[8:9], 0, s[14:15]
	s_waitcnt vmcnt(2)
	s_barrier
	global_load_lds_dwordx4 v[8:9], off
	v_lshl_add_u64 v[6:7], v[6:7], 0, s[14:15]
	s_add_i32 m0, s4, 0x1a000
	s_add_i32 s27, s4, 0x8000
	s_add_i32 s28, s4, 0xa000
	global_load_lds_dwordx4 v[6:7], off
	v_lshl_add_u64 v[4:5], v[4:5], 0, s[14:15]
	s_mov_b32 m0, s27
	s_add_u32 s22, s8, 0x20080
	global_load_lds_dwordx4 v[4:5], off
	v_lshl_add_u64 v[2:3], v[2:3], 0, s[14:15]
	s_mov_b32 m0, s28
	s_addc_u32 s23, s9, 0
	global_load_lds_dwordx4 v[2:3], off
	s_add_i32 m0, s4, 0x1c000
	v_lshl_add_u64 v[2:3], s[22:23], 0, v[62:63]
	global_load_lds_dwordx4 v[2:3], off
	v_lshl_add_u64 v[2:3], s[22:23], 0, v[58:59]
	s_add_i32 m0, s4, 0x1e000
	s_add_u32 s16, s54, s16
	global_load_lds_dwordx4 v[2:3], off
	v_lshlrev_b32_e32 v2, 13, v15
	v_and_b32_e32 v2, 0xffffc000, v2
	v_lshl_add_u32 v2, v14, 10, v2
	v_and_b32_e32 v3, 1, v15
	v_lshl_or_b32 v2, v3, 6, v2
	s_addc_u32 s17, s55, 0
	v_lshl_add_u32 v2, v16, 1, v2
	v_mov_b32_e32 v3, v63
	v_lshl_add_u64 v[2:3], s[16:17], 0, v[2:3]
	s_mov_b64 s[22:23], 0xd018080
	v_lshl_add_u64 v[74:75], v[2:3], 0, s[22:23]
	v_lshlrev_b32_e32 v2, 13, v10
	v_and_b32_e32 v2, 0xffffc000, v2
	s_add_u32 s18, s54, s18
	v_lshl_add_u32 v2, v11, 10, v2
	v_and_b32_e32 v3, 1, v10
	s_addc_u32 s19, s55, 0
	v_lshl_or_b32 v2, v3, 6, v2
	s_add_u32 s29, s18, 0x900100
	s_waitcnt vmcnt(6)
	v_lshl_add_u32 v2, v12, 1, v2
	v_add_u32_e32 v2, 0xffffc000, v2
	v_mov_b32_e32 v3, v63
	s_addc_u32 s30, s19, 0
	s_add_i32 s36, 0, 0x10000
	s_add_i32 s62, 0, 0x14000
	s_add_i32 s64, 0, 0x18000
	s_add_i32 s72, 0, 0x1c000
	v_lshl_add_u64 v[2:3], s[16:17], 0, v[2:3]
	v_add_u32_e32 v79, s36, v13
	v_add_u32_e32 v80, s62, v13
	s_add_i32 s36, s36, s20
	s_add_i32 s62, s62, s20
	v_add_u32_e32 v146, s64, v13
	v_add_u32_e32 v147, s72, v13
	s_add_i32 s64, s64, s20
	s_add_i32 s72, s72, s20
	v_lshl_add_u64 v[76:77], v[2:3], 0, s[22:23]
	s_mov_b32 s31, -2
	s_mov_b64 s[18:19], 0
	v_add_u32_e32 v81, 0, v18
	s_add_i32 s34, s4, 0xc000
	s_add_i32 s35, s4, 0xe000
	s_add_i32 s37, s36, 0x2000
	s_add_i32 s63, s62, 0x2000
	s_add_i32 s65, s64, 0x2000
	s_add_i32 s73, s72, 0x2000
	v_mov_b32_e32 v2, v63
	v_mov_b32_e32 v3, v63
	v_mov_b32_e32 v4, v63
	v_mov_b32_e32 v5, v63
	v_mov_b32_e32 v6, v63
	v_mov_b32_e32 v7, v63
	v_mov_b32_e32 v8, v63
	v_mov_b32_e32 v9, v63
	v_mov_b32_e32 v18, v63
	v_mov_b32_e32 v19, v63
	v_mov_b32_e32 v20, v63
	v_mov_b32_e32 v21, v63
	v_mov_b32_e32 v22, v63
	v_mov_b32_e32 v23, v63
	v_mov_b32_e32 v24, v63
	v_mov_b32_e32 v25, v63
	v_mov_b32_e32 v34, v63
	v_mov_b32_e32 v35, v63
	v_mov_b32_e32 v36, v63
	v_mov_b32_e32 v37, v63
	v_mov_b32_e32 v38, v63
	v_mov_b32_e32 v39, v63
	v_mov_b32_e32 v40, v63
	v_mov_b32_e32 v41, v63
	v_mov_b32_e32 v50, v63
	v_mov_b32_e32 v51, v63
	v_mov_b32_e32 v52, v63
	v_mov_b32_e32 v53, v63
	v_mov_b32_e32 v54, v63
	v_mov_b32_e32 v55, v63
	v_mov_b32_e32 v56, v63
	v_mov_b32_e32 v57, v63
	v_mov_b32_e32 v10, v63
	v_mov_b32_e32 v11, v63
	v_mov_b32_e32 v12, v63
	v_mov_b32_e32 v13, v63
	v_mov_b32_e32 v14, v63
	v_mov_b32_e32 v15, v63
	v_mov_b32_e32 v16, v63
	v_mov_b32_e32 v17, v63
	v_mov_b32_e32 v26, v63
	v_mov_b32_e32 v27, v63
	v_mov_b32_e32 v28, v63
	v_mov_b32_e32 v29, v63
	v_mov_b32_e32 v30, v63
	v_mov_b32_e32 v31, v63
	v_mov_b32_e32 v32, v63
	v_mov_b32_e32 v33, v63
	v_mov_b32_e32 v42, v63
	v_mov_b32_e32 v43, v63
	v_mov_b32_e32 v44, v63
	v_mov_b32_e32 v45, v63
	v_mov_b32_e32 v46, v63
	v_mov_b32_e32 v47, v63
	v_mov_b32_e32 v48, v63
	v_mov_b32_e32 v49, v63
	v_mov_b32_e32 v66, v63
	v_mov_b32_e32 v67, v63
	v_mov_b32_e32 v68, v63
	v_mov_b32_e32 v69, v63
	v_mov_b32_e32 v70, v63
	v_mov_b32_e32 v71, v63
	v_mov_b32_e32 v72, v63
	v_mov_b32_e32 v73, v63
	v_mov_b32_e32 v82, v63
	v_mov_b32_e32 v83, v63
	v_mov_b32_e32 v84, v63
	v_mov_b32_e32 v85, v63
	v_mov_b32_e32 v86, v63
	v_mov_b32_e32 v87, v63
	v_mov_b32_e32 v88, v63
	v_mov_b32_e32 v89, v63
	v_mov_b32_e32 v98, v63
	v_mov_b32_e32 v99, v63
	v_mov_b32_e32 v100, v63
	v_mov_b32_e32 v101, v63
	v_mov_b32_e32 v102, v63
	v_mov_b32_e32 v103, v63
	v_mov_b32_e32 v104, v63
	v_mov_b32_e32 v105, v63
	v_mov_b32_e32 v114, v63
	v_mov_b32_e32 v115, v63
	v_mov_b32_e32 v116, v63
	v_mov_b32_e32 v117, v63
	v_mov_b32_e32 v118, v63
	v_mov_b32_e32 v119, v63
	v_mov_b32_e32 v120, v63
	v_mov_b32_e32 v121, v63
	v_mov_b32_e32 v130, v63
	v_mov_b32_e32 v131, v63
	v_mov_b32_e32 v132, v63
	v_mov_b32_e32 v133, v63
	v_mov_b32_e32 v134, v63
	v_mov_b32_e32 v135, v63
	v_mov_b32_e32 v136, v63
	v_mov_b32_e32 v137, v63
	v_mov_b32_e32 v90, v63
	v_mov_b32_e32 v91, v63
	v_mov_b32_e32 v92, v63
	v_mov_b32_e32 v93, v63
	v_mov_b32_e32 v94, v63
	v_mov_b32_e32 v95, v63
	v_mov_b32_e32 v96, v63
	v_mov_b32_e32 v97, v63
	v_mov_b32_e32 v106, v63
	v_mov_b32_e32 v107, v63
	v_mov_b32_e32 v108, v63
	v_mov_b32_e32 v109, v63
	v_mov_b32_e32 v110, v63
	v_mov_b32_e32 v111, v63
	v_mov_b32_e32 v112, v63
	v_mov_b32_e32 v113, v63
	v_mov_b32_e32 v122, v63
	v_mov_b32_e32 v123, v63
	v_mov_b32_e32 v124, v63
	v_mov_b32_e32 v125, v63
	v_mov_b32_e32 v126, v63
	v_mov_b32_e32 v127, v63
	v_mov_b32_e32 v128, v63
	v_mov_b32_e32 v129, v63
	v_mov_b32_e32 v138, v63
	v_mov_b32_e32 v139, v63
	v_mov_b32_e32 v140, v63
	v_mov_b32_e32 v141, v63
	v_mov_b32_e32 v142, v63
	v_mov_b32_e32 v143, v63
	v_mov_b32_e32 v144, v63
	v_mov_b32_e32 v145, v63
	s_barrier
.LBB0_382:
	ds_read_b128 v[148:151], v79
	ds_read_b128 v[152:155], v79 offset:1024
	ds_read_b128 v[156:159], v79 offset:2048
	ds_read_b128 v[160:163], v79 offset:3072
	ds_read_b128 v[164:167], v80
	ds_read_b128 v[168:171], v80 offset:1024
	ds_read_b128 v[172:175], v80 offset:2048
	ds_read_b128 v[176:179], v80 offset:3072
	s_add_u32 s20, s16, s18
	s_addc_u32 s21, s17, s19
	s_add_u32 s20, s20, 0xd000100
	s_addc_u32 s21, s21, 0
	s_add_u32 s74, s29, s18
	s_addc_u32 s75, s30, s19
	s_cmpk_eq_i32 s18, 0x300
	s_cselect_b32 s23, s11, s21
	s_cselect_b32 s22, s10, s20
	s_cselect_b32 s21, s9, s75
	s_cselect_b32 s20, s8, s74
	s_mov_b32 m0, s34
	v_lshl_add_u64 v[212:213], v[74:75], 0, s[18:19]
	ds_read_b128 v[180:183], v81
	ds_read_b128 v[184:187], v81 offset:1024
	ds_read_b128 v[188:191], v81 offset:2048
	ds_read_b128 v[192:195], v81 offset:3072
	ds_read_b128 v[196:199], v81 offset:4096
	ds_read_b128 v[200:203], v81 offset:5120
	global_load_lds_dwordx4 v[212:213], off
	v_lshl_add_u64 v[212:213], v[76:77], 0, s[18:19]
	s_mov_b32 m0, s35
	s_nop 0
	global_load_lds_dwordx4 v[212:213], off
	s_waitcnt vmcnt(8)
	s_waitcnt lgkmcnt(0)
	s_barrier
	s_setprio 1
	s_waitcnt lgkmcnt(0)
	v_mfma_f32_16x16x32_bf16 v[142:145], v[148:151], v[180:183], v[142:145]
	v_mfma_f32_16x16x32_bf16 v[138:141], v[156:159], v[180:183], v[138:141]
	v_mfma_f32_16x16x32_bf16 v[126:129], v[148:151], v[188:191], v[126:129]
	v_mfma_f32_16x16x32_bf16 v[122:125], v[156:159], v[188:191], v[122:125]
	v_mfma_f32_16x16x32_bf16 v[110:113], v[148:151], v[196:199], v[110:113]
	v_mfma_f32_16x16x32_bf16 v[106:109], v[156:159], v[196:199], v[106:109]
	v_mfma_f32_16x16x32_bf16 v[142:145], v[152:155], v[184:187], v[142:145]
	v_mfma_f32_16x16x32_bf16 v[138:141], v[160:163], v[184:187], v[138:141]
	v_mfma_f32_16x16x32_bf16 v[126:129], v[152:155], v[192:195], v[126:129]
	v_mfma_f32_16x16x32_bf16 v[122:125], v[160:163], v[192:195], v[122:125]
	v_mfma_f32_16x16x32_bf16 v[110:113], v[152:155], v[200:203], v[110:113]
	v_mfma_f32_16x16x32_bf16 v[106:109], v[160:163], v[200:203], v[106:109]
	s_setprio 0
	s_setprio 1
	v_mfma_f32_16x16x32_bf16 v[134:137], v[164:167], v[180:183], v[134:137]
	v_mfma_f32_16x16x32_bf16 v[130:133], v[172:175], v[180:183], v[130:133]
	v_mfma_f32_16x16x32_bf16 v[118:121], v[164:167], v[188:191], v[118:121]
	v_mfma_f32_16x16x32_bf16 v[114:117], v[172:175], v[188:191], v[114:117]
	v_mfma_f32_16x16x32_bf16 v[102:105], v[164:167], v[196:199], v[102:105]
	v_mfma_f32_16x16x32_bf16 v[98:101], v[172:175], v[196:199], v[98:101]
	v_mfma_f32_16x16x32_bf16 v[134:137], v[168:171], v[184:187], v[134:137]
	v_mfma_f32_16x16x32_bf16 v[130:133], v[176:179], v[184:187], v[130:133]
	v_mfma_f32_16x16x32_bf16 v[118:121], v[168:171], v[192:195], v[118:121]
	v_mfma_f32_16x16x32_bf16 v[114:117], v[176:179], v[192:195], v[114:117]
	v_mfma_f32_16x16x32_bf16 v[102:105], v[168:171], v[200:203], v[102:105]
	v_mfma_f32_16x16x32_bf16 v[98:101], v[176:179], v[200:203], v[98:101]
	s_setprio 0
	s_barrier
	s_mov_b32 m0, s36
	v_lshl_add_u64 v[212:213], s[20:21], 0, v[62:63]
	s_add_u32 s74, s20, 0x20000
	ds_read_b128 v[180:183], v81 offset:16384
	ds_read_b128 v[184:187], v81 offset:17408
	ds_read_b128 v[188:191], v81 offset:18432
	ds_read_b128 v[192:195], v81 offset:19456
	ds_read_b128 v[196:199], v81 offset:20480
	ds_read_b128 v[200:203], v81 offset:21504
	global_load_lds_dwordx4 v[212:213], off
	v_lshl_add_u64 v[216:217], s[20:21], 0, v[58:59]
	s_mov_b32 m0, s37
	s_addc_u32 s75, s21, 0
	global_load_lds_dwordx4 v[216:217], off
	v_lshl_add_u64 v[218:219], s[74:75], 0, v[62:63]
	s_mov_b32 m0, s62
	v_lshl_add_u64 v[220:221], s[22:23], 0, v[60:61]
	global_load_lds_dwordx4 v[218:219], off
	v_lshl_add_u64 v[218:219], s[74:75], 0, v[58:59]
	s_mov_b32 m0, s63
	s_nop 0
	global_load_lds_dwordx4 v[218:219], off
	v_lshl_add_u64 v[218:219], s[22:23], 0, v[64:65]
	s_mov_b32 m0, s4
	s_nop 0
	global_load_lds_dwordx4 v[218:219], off
	s_mov_b32 m0, s5
	s_nop 0
	global_load_lds_dwordx4 v[220:221], off
	s_waitcnt vmcnt(8)
	s_waitcnt lgkmcnt(0)
	s_barrier
	s_setprio 1
	s_waitcnt lgkmcnt(0)
	v_mfma_f32_16x16x32_bf16 v[70:73], v[148:151], v[180:183], v[70:73]
	v_mfma_f32_16x16x32_bf16 v[66:69], v[156:159], v[180:183], v[66:69]
	v_mfma_f32_16x16x32_bf16 v[46:49], v[148:151], v[188:191], v[46:49]
	v_mfma_f32_16x16x32_bf16 v[42:45], v[156:159], v[188:191], v[42:45]
	v_mfma_f32_16x16x32_bf16 v[30:33], v[148:151], v[196:199], v[30:33]
	v_mfma_f32_16x16x32_bf16 v[26:29], v[156:159], v[196:199], v[26:29]
	v_mfma_f32_16x16x32_bf16 v[70:73], v[152:155], v[184:187], v[70:73]
	v_mfma_f32_16x16x32_bf16 v[66:69], v[160:163], v[184:187], v[66:69]
	v_mfma_f32_16x16x32_bf16 v[46:49], v[152:155], v[192:195], v[46:49]
	v_mfma_f32_16x16x32_bf16 v[42:45], v[160:163], v[192:195], v[42:45]
	v_mfma_f32_16x16x32_bf16 v[30:33], v[152:155], v[200:203], v[30:33]
	v_mfma_f32_16x16x32_bf16 v[26:29], v[160:163], v[200:203], v[26:29]
	s_setprio 0
	s_setprio 1
	v_mfma_f32_16x16x32_bf16 v[54:57], v[164:167], v[180:183], v[54:57]
	v_mfma_f32_16x16x32_bf16 v[50:53], v[172:175], v[180:183], v[50:53]
	v_mfma_f32_16x16x32_bf16 v[38:41], v[164:167], v[188:191], v[38:41]
	v_mfma_f32_16x16x32_bf16 v[34:37], v[172:175], v[188:191], v[34:37]
	v_mfma_f32_16x16x32_bf16 v[22:25], v[164:167], v[196:199], v[22:25]
	v_mfma_f32_16x16x32_bf16 v[18:21], v[172:175], v[196:199], v[18:21]
	v_mfma_f32_16x16x32_bf16 v[54:57], v[168:171], v[184:187], v[54:57]
	v_mfma_f32_16x16x32_bf16 v[50:53], v[176:179], v[184:187], v[50:53]
	v_mfma_f32_16x16x32_bf16 v[38:41], v[168:171], v[192:195], v[38:41]
	v_mfma_f32_16x16x32_bf16 v[34:37], v[176:179], v[192:195], v[34:37]
	v_mfma_f32_16x16x32_bf16 v[22:25], v[168:171], v[200:203], v[22:25]
	v_mfma_f32_16x16x32_bf16 v[18:21], v[176:179], v[200:203], v[18:21]
	s_setprio 0
	s_barrier
	ds_read_b128 v[148:151], v146
	ds_read_b128 v[152:155], v146 offset:1024
	ds_read_b128 v[156:159], v146 offset:2048
	ds_read_b128 v[160:163], v146 offset:3072
	ds_read_b128 v[164:167], v147
	ds_read_b128 v[168:171], v147 offset:1024
	ds_read_b128 v[172:175], v147 offset:2048
	ds_read_b128 v[176:179], v147 offset:3072
	s_add_u32 s22, s22, 0x18000
	s_addc_u32 s23, s23, 0
	s_mov_b32 m0, s24
	v_lshl_add_u64 v[222:223], s[22:23], 0, v[64:65]
	ds_read_b128 v[180:183], v81 offset:32768
	ds_read_b128 v[184:187], v81 offset:33792
	ds_read_b128 v[188:191], v81 offset:34816
	ds_read_b128 v[192:195], v81 offset:35840
	ds_read_b128 v[196:199], v81 offset:36864
	ds_read_b128 v[200:203], v81 offset:37888
	global_load_lds_dwordx4 v[222:223], off
	v_lshl_add_u64 v[222:223], s[22:23], 0, v[60:61]
	s_mov_b32 m0, s25
	s_nop 0
	global_load_lds_dwordx4 v[222:223], off
	s_waitcnt vmcnt(8)
	s_waitcnt lgkmcnt(0)
	s_barrier
	s_setprio 1
	s_waitcnt lgkmcnt(0)
	v_mfma_f32_16x16x32_bf16 v[142:145], v[148:151], v[180:183], v[142:145]
	v_mfma_f32_16x16x32_bf16 v[138:141], v[156:159], v[180:183], v[138:141]
	v_mfma_f32_16x16x32_bf16 v[126:129], v[148:151], v[188:191], v[126:129]
	v_mfma_f32_16x16x32_bf16 v[122:125], v[156:159], v[188:191], v[122:125]
	v_mfma_f32_16x16x32_bf16 v[110:113], v[148:151], v[196:199], v[110:113]
	v_mfma_f32_16x16x32_bf16 v[106:109], v[156:159], v[196:199], v[106:109]
	v_mfma_f32_16x16x32_bf16 v[142:145], v[152:155], v[184:187], v[142:145]
	v_mfma_f32_16x16x32_bf16 v[138:141], v[160:163], v[184:187], v[138:141]
	v_mfma_f32_16x16x32_bf16 v[126:129], v[152:155], v[192:195], v[126:129]
	v_mfma_f32_16x16x32_bf16 v[122:125], v[160:163], v[192:195], v[122:125]
	v_mfma_f32_16x16x32_bf16 v[110:113], v[152:155], v[200:203], v[110:113]
	v_mfma_f32_16x16x32_bf16 v[106:109], v[160:163], v[200:203], v[106:109]
	s_setprio 0
	s_setprio 1
	v_mfma_f32_16x16x32_bf16 v[134:137], v[164:167], v[180:183], v[134:137]
	v_mfma_f32_16x16x32_bf16 v[130:133], v[172:175], v[180:183], v[130:133]
	v_mfma_f32_16x16x32_bf16 v[118:121], v[164:167], v[188:191], v[118:121]
	v_mfma_f32_16x16x32_bf16 v[114:117], v[172:175], v[188:191], v[114:117]
	v_mfma_f32_16x16x32_bf16 v[102:105], v[164:167], v[196:199], v[102:105]
	v_mfma_f32_16x16x32_bf16 v[98:101], v[172:175], v[196:199], v[98:101]
	v_mfma_f32_16x16x32_bf16 v[134:137], v[168:171], v[184:187], v[134:137]
	v_mfma_f32_16x16x32_bf16 v[130:133], v[176:179], v[184:187], v[130:133]
	v_mfma_f32_16x16x32_bf16 v[118:121], v[168:171], v[192:195], v[118:121]
	v_mfma_f32_16x16x32_bf16 v[114:117], v[176:179], v[192:195], v[114:117]
	v_mfma_f32_16x16x32_bf16 v[102:105], v[168:171], v[200:203], v[102:105]
	v_mfma_f32_16x16x32_bf16 v[98:101], v[176:179], v[200:203], v[98:101]
	s_setprio 0
	s_barrier
	s_mov_b32 m0, s64
	v_lshl_add_u64 v[212:213], v[212:213], 0, s[14:15]
	s_add_u32 s20, s20, 0x20080
	ds_read_b128 v[180:183], v81 offset:49152
	ds_read_b128 v[184:187], v81 offset:50176
	ds_read_b128 v[188:191], v81 offset:51200
	ds_read_b128 v[192:195], v81 offset:52224
	ds_read_b128 v[196:199], v81 offset:53248
	ds_read_b128 v[200:203], v81 offset:54272
	global_load_lds_dwordx4 v[212:213], off
	v_lshl_add_u64 v[212:213], v[216:217], 0, s[14:15]
	s_mov_b32 m0, s65
	s_addc_u32 s21, s21, 0
	global_load_lds_dwordx4 v[212:213], off
	v_lshl_add_u64 v[212:213], s[20:21], 0, v[62:63]
	s_mov_b32 m0, s72
	s_nop 0
	global_load_lds_dwordx4 v[212:213], off
	v_lshl_add_u64 v[212:213], s[20:21], 0, v[58:59]
	s_mov_b32 m0, s73
	s_nop 0
	global_load_lds_dwordx4 v[212:213], off
	v_lshl_add_u64 v[212:213], v[218:219], 0, s[14:15]
	s_mov_b32 m0, s27
	s_nop 0
	global_load_lds_dwordx4 v[212:213], off
	v_lshl_add_u64 v[212:213], v[220:221], 0, s[14:15]
	s_mov_b32 m0, s28
	s_nop 0
	global_load_lds_dwordx4 v[212:213], off
	s_waitcnt vmcnt(8)
	s_waitcnt lgkmcnt(0)
	s_barrier
	s_setprio 1
	s_waitcnt lgkmcnt(0)
	v_mfma_f32_16x16x32_bf16 v[70:73], v[148:151], v[180:183], v[70:73]
	v_mfma_f32_16x16x32_bf16 v[66:69], v[156:159], v[180:183], v[66:69]
	v_mfma_f32_16x16x32_bf16 v[46:49], v[148:151], v[188:191], v[46:49]
	v_mfma_f32_16x16x32_bf16 v[42:45], v[156:159], v[188:191], v[42:45]
	v_mfma_f32_16x16x32_bf16 v[30:33], v[148:151], v[196:199], v[30:33]
	v_mfma_f32_16x16x32_bf16 v[26:29], v[156:159], v[196:199], v[26:29]
	v_mfma_f32_16x16x32_bf16 v[70:73], v[152:155], v[184:187], v[70:73]
	v_mfma_f32_16x16x32_bf16 v[66:69], v[160:163], v[184:187], v[66:69]
	v_mfma_f32_16x16x32_bf16 v[46:49], v[152:155], v[192:195], v[46:49]
	v_mfma_f32_16x16x32_bf16 v[42:45], v[160:163], v[192:195], v[42:45]
	v_mfma_f32_16x16x32_bf16 v[30:33], v[152:155], v[200:203], v[30:33]
	v_mfma_f32_16x16x32_bf16 v[26:29], v[160:163], v[200:203], v[26:29]
	s_setprio 0
	s_setprio 1
	v_mfma_f32_16x16x32_bf16 v[54:57], v[164:167], v[180:183], v[54:57]
	v_mfma_f32_16x16x32_bf16 v[50:53], v[172:175], v[180:183], v[50:53]
	v_mfma_f32_16x16x32_bf16 v[38:41], v[164:167], v[188:191], v[38:41]
	v_mfma_f32_16x16x32_bf16 v[34:37], v[172:175], v[188:191], v[34:37]
	v_mfma_f32_16x16x32_bf16 v[22:25], v[164:167], v[196:199], v[22:25]
	v_mfma_f32_16x16x32_bf16 v[18:21], v[172:175], v[196:199], v[18:21]
	v_mfma_f32_16x16x32_bf16 v[54:57], v[168:171], v[184:187], v[54:57]
	v_mfma_f32_16x16x32_bf16 v[50:53], v[176:179], v[184:187], v[50:53]
	v_mfma_f32_16x16x32_bf16 v[38:41], v[168:171], v[192:195], v[38:41]
	v_mfma_f32_16x16x32_bf16 v[34:37], v[176:179], v[192:195], v[34:37]
	v_mfma_f32_16x16x32_bf16 v[22:25], v[168:171], v[200:203], v[22:25]
	v_mfma_f32_16x16x32_bf16 v[18:21], v[176:179], v[200:203], v[18:21]
	s_setprio 0
	s_barrier
	s_add_i32 s31, s31, 2
	s_add_u32 s18, s18, 0x100
	s_addc_u32 s19, s19, 0
	s_cmp_gt_u32 s31, 5
	s_cbranch_scc0 .LBB0_382
	s_cmpk_lt_u32 s0, 0x100
	s_cbranch_scc0 .LBB0_385
	s_barrier
.LBB0_385:
	s_and_b64 s[4:5], s[6:7], exec
	s_cselect_b32 s0, 0x100, 0
	v_or_b32_e32 v58, s0, v78
	v_or_b32_e32 v60, s26, v58
	v_readlane_b32 s4, v242, 16
	v_lshlrev_b32_e32 v62, 2, v60
	v_readlane_b32 s12, v242, 24
	v_readlane_b32 s13, v242, 25
	s_nop 4
	global_load_dwordx4 v[74:77], v62, s[12:13] offset:16
	global_load_dwordx4 v[78:81], v62, s[12:13]
	v_add_u32_e32 v148, s99, v1
	v_ashrrev_i32_e32 v149, 31, v148
	v_lshlrev_b64 v[58:59], 10, v[148:149]
	v_lshl_add_u64 v[58:59], s[80:81], 0, v[58:59]
	v_lshlrev_b32_e32 v146, 1, v60
	v_mov_b32_e32 v147, 0
	v_lshl_add_u64 v[154:155], v[58:59], 0, v[146:147]
	global_load_dwordx4 v[150:153], v[154:155], off
	global_load_dwordx4 v[58:61], v62, s[12:13] offset:528
	s_nop 0
	global_load_dwordx4 v[62:65], v62, s[12:13] offset:512
	v_readlane_b32 s5, v242, 17
	v_readlane_b32 s6, v242, 18
	v_readlane_b32 s7, v242, 19
	v_readlane_b32 s8, v242, 20
	v_readlane_b32 s9, v242, 21
	v_readlane_b32 s10, v242, 22
	v_readlane_b32 s11, v242, 23
	v_readlane_b32 s14, v242, 26
	v_readlane_b32 s15, v242, 27
	v_readlane_b32 s16, v242, 28
	v_readlane_b32 s17, v242, 29
	v_readlane_b32 s18, v242, 30
	v_readlane_b32 s19, v242, 31
	s_waitcnt vmcnt(0)
	v_add_f32_e32 v138, v138, v74
	v_add_f32_e32 v1, v142, v78
	v_add_f32_e32 v142, v143, v79
	v_add_f32_e32 v139, v139, v75
	v_add_f32_e32 v143, v144, v80
	v_add_f32_e32 v140, v140, v76
	v_add_f32_e32 v144, v145, v81
	v_add_f32_e32 v141, v141, v77
	v_mul_f32_e32 v1, 0xbfb8aa3b, v1
	v_mul_f32_e32 v138, 0xbfb8aa3b, v138
	v_mul_f32_e32 v142, 0xbfb8aa3b, v142
	v_mul_f32_e32 v139, 0xbfb8aa3b, v139
	v_mul_f32_e32 v143, 0xbfb8aa3b, v143
	v_mul_f32_e32 v140, 0xbfb8aa3b, v140
	v_mul_f32_e32 v144, 0xbfb8aa3b, v144
	v_mul_f32_e32 v141, 0xbfb8aa3b, v141
	v_exp_f32_e32 v1, v1
	v_exp_f32_e32 v138, v138
	v_exp_f32_e32 v142, v142
	v_exp_f32_e32 v139, v139
	v_exp_f32_e32 v143, v143
	v_exp_f32_e32 v140, v140
	v_exp_f32_e32 v144, v144
	v_exp_f32_e32 v141, v141
	v_add_f32_e32 v1, 1.0, v1
	v_add_f32_e32 v138, 1.0, v138
	v_add_f32_e32 v142, 1.0, v142
	v_add_f32_e32 v139, 1.0, v139
	v_add_f32_e32 v143, 1.0, v143
	v_add_f32_e32 v140, 1.0, v140
	v_add_f32_e32 v144, 1.0, v144
	v_add_f32_e32 v141, 1.0, v141
	v_rcp_f32_e32 v1, v1
	v_rcp_f32_e32 v138, v138
	v_rcp_f32_e32 v142, v142
	v_rcp_f32_e32 v139, v139
	v_rcp_f32_e32 v143, v143
	v_rcp_f32_e32 v140, v140
	v_rcp_f32_e32 v144, v144
	v_rcp_f32_e32 v141, v141
	v_lshlrev_b32_e32 v145, 16, v150
	v_and_b32_e32 v150, 0xffff0000, v150
	v_lshlrev_b32_e32 v156, 16, v151
	v_and_b32_e32 v151, 0xffff0000, v151
	v_lshlrev_b32_e32 v157, 16, v152
	v_and_b32_e32 v152, 0xffff0000, v152
	v_lshlrev_b32_e32 v158, 16, v153
	v_and_b32_e32 v153, 0xffff0000, v153
	v_mul_f32_e32 v1, v1, v145
	v_mul_f32_e32 v145, v138, v157
	v_mul_f32_e32 v138, v142, v150
	v_mul_f32_e32 v142, v139, v152
	v_mul_f32_e32 v139, v143, v156
	v_mul_f32_e32 v143, v140, v158
	v_mul_f32_e32 v140, v144, v151
	v_mul_f32_e32 v141, v141, v153
	v_cvt_pk_bf16_f32 v138, v1, v138
	v_cvt_pk_bf16_f32 v139, v139, v140
	v_cvt_pk_bf16_f32 v140, v145, v142
	v_cvt_pk_bf16_f32 v141, v143, v141
	global_load_dwordx4 v[142:145], v[154:155], off offset:256
	v_add_f32_e32 v1, v134, v62
	v_add_f32_e32 v130, v130, v58
	v_add_f32_e32 v134, v135, v63
	v_add_f32_e32 v131, v131, v59
	v_add_f32_e32 v135, v136, v64
	v_add_f32_e32 v132, v132, v60
	v_add_f32_e32 v136, v137, v65
	v_add_f32_e32 v133, v133, v61
	v_mul_f32_e32 v1, 0xbfb8aa3b, v1
	v_mul_f32_e32 v130, 0xbfb8aa3b, v130
	v_mul_f32_e32 v134, 0xbfb8aa3b, v134
	v_mul_f32_e32 v131, 0xbfb8aa3b, v131
	v_mul_f32_e32 v135, 0xbfb8aa3b, v135
	v_mul_f32_e32 v132, 0xbfb8aa3b, v132
	v_mul_f32_e32 v136, 0xbfb8aa3b, v136
	v_mul_f32_e32 v133, 0xbfb8aa3b, v133
	v_exp_f32_e32 v1, v1
	v_exp_f32_e32 v130, v130
	v_exp_f32_e32 v134, v134
	v_exp_f32_e32 v131, v131
	v_exp_f32_e32 v135, v135
	v_exp_f32_e32 v132, v132
	v_exp_f32_e32 v136, v136
	v_exp_f32_e32 v133, v133
	v_add_f32_e32 v1, 1.0, v1
	v_add_f32_e32 v130, 1.0, v130
	v_add_f32_e32 v134, 1.0, v134
	v_add_f32_e32 v131, 1.0, v131
	v_add_f32_e32 v135, 1.0, v135
	v_add_f32_e32 v132, 1.0, v132
	v_add_f32_e32 v136, 1.0, v136
	v_add_f32_e32 v133, 1.0, v133
	v_add_u32_e32 v150, 16, v148
	v_lshlrev_b64 v[152:153], 11, v[148:149]
	v_rcp_f32_e32 v1, v1
	v_rcp_f32_e32 v130, v130
	v_rcp_f32_e32 v134, v134
	v_rcp_f32_e32 v131, v131
	v_rcp_f32_e32 v135, v135
	v_rcp_f32_e32 v132, v132
	v_rcp_f32_e32 v136, v136
	v_rcp_f32_e32 v133, v133
	v_ashrrev_i32_e32 v151, 31, v150
	v_lshl_add_u64 v[152:153], s[60:61], 0, v[152:153]
	v_lshlrev_b64 v[154:155], 10, v[150:151]
	v_lshl_add_u64 v[152:153], v[152:153], 0, v[146:147]
	v_lshl_add_u64 v[154:155], s[80:81], 0, v[154:155]
	global_store_dwordx4 v[152:153], v[138:141], off offset:1024
	v_lshl_add_u64 v[154:155], v[154:155], 0, v[146:147]
	v_add_f32_e32 v122, v122, v74
	v_add_f32_e32 v123, v123, v75
	v_add_f32_e32 v124, v124, v76
	v_add_f32_e32 v125, v125, v77
	v_mul_f32_e32 v122, 0xbfb8aa3b, v122
	v_mul_f32_e32 v123, 0xbfb8aa3b, v123
	v_mul_f32_e32 v124, 0xbfb8aa3b, v124
	v_mul_f32_e32 v125, 0xbfb8aa3b, v125
	v_exp_f32_e32 v122, v122
	v_exp_f32_e32 v123, v123
	v_exp_f32_e32 v124, v124
	v_exp_f32_e32 v125, v125
	v_add_f32_e32 v122, 1.0, v122
	v_add_f32_e32 v123, 1.0, v123
	v_add_f32_e32 v124, 1.0, v124
	v_add_f32_e32 v125, 1.0, v125
	v_rcp_f32_e32 v122, v122
	v_rcp_f32_e32 v123, v123
	v_rcp_f32_e32 v124, v124
	v_rcp_f32_e32 v125, v125
	v_add_f32_e32 v114, v114, v58
	v_add_f32_e32 v115, v115, v59
	v_add_f32_e32 v116, v116, v60
	v_add_f32_e32 v117, v117, v61
	v_mul_f32_e32 v114, 0xbfb8aa3b, v114
	v_mul_f32_e32 v115, 0xbfb8aa3b, v115
	v_mul_f32_e32 v116, 0xbfb8aa3b, v116
	v_mul_f32_e32 v117, 0xbfb8aa3b, v117
	v_exp_f32_e32 v114, v114
	v_exp_f32_e32 v115, v115
	s_waitcnt vmcnt(1)
	v_lshlrev_b32_e32 v137, 16, v142
	v_and_b32_e32 v138, 0xffff0000, v142
	v_lshlrev_b32_e32 v139, 16, v143
	v_and_b32_e32 v140, 0xffff0000, v143
	v_lshlrev_b32_e32 v141, 16, v144
	v_and_b32_e32 v142, 0xffff0000, v144
	v_lshlrev_b32_e32 v143, 16, v145
	v_and_b32_e32 v144, 0xffff0000, v145
	v_mul_f32_e32 v1, v1, v137
	v_mul_f32_e32 v137, v130, v141
	v_mul_f32_e32 v130, v134, v138
	v_mul_f32_e32 v134, v131, v142
	v_mul_f32_e32 v131, v135, v139
	v_mul_f32_e32 v135, v132, v143
	v_mul_f32_e32 v132, v136, v140
	v_mul_f32_e32 v133, v133, v144
	v_cvt_pk_bf16_f32 v130, v1, v130
	v_cvt_pk_bf16_f32 v131, v131, v132
	v_cvt_pk_bf16_f32 v132, v137, v134
	v_cvt_pk_bf16_f32 v133, v135, v133
	global_load_dwordx4 v[134:137], v[154:155], off
	v_add_f32_e32 v1, v126, v78
	v_add_f32_e32 v126, v127, v79
	v_add_f32_e32 v127, v128, v80
	v_add_f32_e32 v128, v129, v81
	v_mul_f32_e32 v1, 0xbfb8aa3b, v1
	v_mul_f32_e32 v126, 0xbfb8aa3b, v126
	v_mul_f32_e32 v127, 0xbfb8aa3b, v127
	v_mul_f32_e32 v128, 0xbfb8aa3b, v128
	v_exp_f32_e32 v1, v1
	v_exp_f32_e32 v126, v126
	v_exp_f32_e32 v127, v127
	v_exp_f32_e32 v128, v128
	v_add_f32_e32 v1, 1.0, v1
	v_add_f32_e32 v126, 1.0, v126
	v_add_f32_e32 v127, 1.0, v127
	v_add_f32_e32 v128, 1.0, v128
	v_rcp_f32_e32 v1, v1
	v_rcp_f32_e32 v126, v126
	v_rcp_f32_e32 v127, v127
	v_rcp_f32_e32 v128, v128
	global_store_dwordx4 v[152:153], v[130:133], off offset:1280
	v_exp_f32_e32 v116, v116
	v_exp_f32_e32 v117, v117
	v_add_f32_e32 v114, 1.0, v114
	v_add_f32_e32 v115, 1.0, v115
	v_add_f32_e32 v116, 1.0, v116
	v_add_f32_e32 v117, 1.0, v117
	v_rcp_f32_e32 v114, v114
	v_rcp_f32_e32 v115, v115
	v_rcp_f32_e32 v116, v116
	v_rcp_f32_e32 v117, v117
	v_add_f32_e32 v106, v106, v74
	v_add_f32_e32 v107, v107, v75
	v_add_f32_e32 v108, v108, v76
	v_add_f32_e32 v109, v109, v77
	v_mul_f32_e32 v106, 0xbfb8aa3b, v106
	v_mul_f32_e32 v107, 0xbfb8aa3b, v107
	v_mul_f32_e32 v108, 0xbfb8aa3b, v108
	v_mul_f32_e32 v109, 0xbfb8aa3b, v109
	v_exp_f32_e32 v106, v106
	v_exp_f32_e32 v107, v107
	v_exp_f32_e32 v108, v108
	v_exp_f32_e32 v109, v109
	v_add_f32_e32 v106, 1.0, v106
	v_add_f32_e32 v107, 1.0, v107
	v_add_f32_e32 v108, 1.0, v108
	v_add_f32_e32 v109, 1.0, v109
	v_rcp_f32_e32 v106, v106
	v_rcp_f32_e32 v107, v107
	v_rcp_f32_e32 v108, v108
	v_rcp_f32_e32 v109, v109
	v_add_f32_e32 v98, v98, v58
	v_add_f32_e32 v99, v99, v59
	v_add_f32_e32 v100, v100, v60
	v_add_f32_e32 v101, v101, v61
	v_mul_f32_e32 v98, 0xbfb8aa3b, v98
	v_mul_f32_e32 v99, 0xbfb8aa3b, v99
	v_mul_f32_e32 v100, 0xbfb8aa3b, v100
	v_mul_f32_e32 v101, 0xbfb8aa3b, v101
	v_exp_f32_e32 v98, v98
	v_exp_f32_e32 v99, v99
	v_exp_f32_e32 v100, v100
	v_exp_f32_e32 v101, v101
	v_add_f32_e32 v98, 1.0, v98
	v_add_f32_e32 v99, 1.0, v99
	v_add_f32_e32 v100, 1.0, v100
	v_add_f32_e32 v101, 1.0, v101
	v_rcp_f32_e32 v98, v98
	v_rcp_f32_e32 v99, v99
	v_rcp_f32_e32 v100, v100
	v_rcp_f32_e32 v101, v101
	v_add_f32_e32 v90, v90, v74
	v_add_f32_e32 v91, v91, v75
	v_add_f32_e32 v92, v92, v76
	v_add_f32_e32 v93, v93, v77
	v_mul_f32_e32 v90, 0xbfb8aa3b, v90
	v_mul_f32_e32 v91, 0xbfb8aa3b, v91
	v_mul_f32_e32 v92, 0xbfb8aa3b, v92
	v_mul_f32_e32 v93, 0xbfb8aa3b, v93
	s_waitcnt vmcnt(1)
	v_lshlrev_b32_e32 v129, 16, v134
	v_and_b32_e32 v130, 0xffff0000, v134
	v_lshlrev_b32_e32 v131, 16, v135
	v_and_b32_e32 v132, 0xffff0000, v135
	v_lshlrev_b32_e32 v133, 16, v136
	v_and_b32_e32 v134, 0xffff0000, v136
	v_lshlrev_b32_e32 v135, 16, v137
	v_and_b32_e32 v136, 0xffff0000, v137
	v_mul_f32_e32 v1, v1, v129
	v_mul_f32_e32 v129, v122, v133
	v_mul_f32_e32 v122, v126, v130
	v_mul_f32_e32 v126, v123, v134
	v_mul_f32_e32 v123, v127, v131
	v_mul_f32_e32 v127, v124, v135
	v_mul_f32_e32 v124, v128, v132
	v_mul_f32_e32 v125, v125, v136
	v_cvt_pk_bf16_f32 v122, v1, v122
	v_cvt_pk_bf16_f32 v123, v123, v124
	v_cvt_pk_bf16_f32 v124, v129, v126
	v_cvt_pk_bf16_f32 v125, v127, v125
	global_load_dwordx4 v[126:129], v[154:155], off offset:256
	v_add_f32_e32 v1, v118, v62
	v_add_f32_e32 v118, v119, v63
	v_add_f32_e32 v119, v120, v64
	v_add_f32_e32 v120, v121, v65
	v_mul_f32_e32 v1, 0xbfb8aa3b, v1
	v_mul_f32_e32 v118, 0xbfb8aa3b, v118
	v_mul_f32_e32 v119, 0xbfb8aa3b, v119
	v_mul_f32_e32 v120, 0xbfb8aa3b, v120
	v_exp_f32_e32 v1, v1
	v_exp_f32_e32 v118, v118
	v_exp_f32_e32 v119, v119
	v_exp_f32_e32 v120, v120
	v_add_f32_e32 v1, 1.0, v1
	v_add_f32_e32 v118, 1.0, v118
	v_add_f32_e32 v119, 1.0, v119
	v_add_f32_e32 v120, 1.0, v120
	v_add_u32_e32 v130, 32, v148
	v_lshlrev_b64 v[132:133], 11, v[150:151]
	v_rcp_f32_e32 v1, v1
	v_rcp_f32_e32 v118, v118
	v_rcp_f32_e32 v119, v119
	v_rcp_f32_e32 v120, v120
	v_ashrrev_i32_e32 v131, 31, v130
	v_lshl_add_u64 v[132:133], s[60:61], 0, v[132:133]
	v_lshlrev_b64 v[134:135], 10, v[130:131]
	v_lshl_add_u64 v[132:133], v[132:133], 0, v[146:147]
	v_lshl_add_u64 v[134:135], s[80:81], 0, v[134:135]
	global_store_dwordx4 v[132:133], v[122:125], off offset:1024
	v_lshl_add_u64 v[134:135], v[134:135], 0, v[146:147]
	v_exp_f32_e32 v90, v90
	v_exp_f32_e32 v91, v91
	v_exp_f32_e32 v92, v92
	v_exp_f32_e32 v93, v93
	v_add_f32_e32 v90, 1.0, v90
	v_add_f32_e32 v91, 1.0, v91
	v_add_f32_e32 v92, 1.0, v92
	v_add_f32_e32 v93, 1.0, v93
	v_rcp_f32_e32 v90, v90
	v_rcp_f32_e32 v91, v91
	v_rcp_f32_e32 v92, v92
	v_rcp_f32_e32 v93, v93
	v_add_f32_e32 v82, v82, v58
	v_add_f32_e32 v83, v83, v59
	v_add_f32_e32 v84, v84, v60
	v_add_f32_e32 v85, v85, v61
	v_mul_f32_e32 v82, 0xbfb8aa3b, v82
	v_mul_f32_e32 v83, 0xbfb8aa3b, v83
	v_mul_f32_e32 v84, 0xbfb8aa3b, v84
	v_mul_f32_e32 v85, 0xbfb8aa3b, v85
	v_exp_f32_e32 v82, v82
	v_exp_f32_e32 v83, v83
	v_exp_f32_e32 v84, v84
	v_exp_f32_e32 v85, v85
	v_add_f32_e32 v82, 1.0, v82
	v_add_f32_e32 v83, 1.0, v83
	v_add_f32_e32 v84, 1.0, v84
	v_add_f32_e32 v85, 1.0, v85
	v_rcp_f32_e32 v82, v82
	v_rcp_f32_e32 v83, v83
	v_rcp_f32_e32 v84, v84
	v_rcp_f32_e32 v85, v85
	v_add_f32_e32 v66, v66, v74
	v_add_f32_e32 v67, v67, v75
	v_add_f32_e32 v68, v68, v76
	v_add_f32_e32 v69, v69, v77
	v_mul_f32_e32 v66, 0xbfb8aa3b, v66
	v_mul_f32_e32 v67, 0xbfb8aa3b, v67
	v_mul_f32_e32 v68, 0xbfb8aa3b, v68
	v_mul_f32_e32 v69, 0xbfb8aa3b, v69
	v_exp_f32_e32 v66, v66
	v_exp_f32_e32 v67, v67
	v_exp_f32_e32 v68, v68
	v_exp_f32_e32 v69, v69
	v_add_f32_e32 v66, 1.0, v66
	v_add_f32_e32 v67, 1.0, v67
	v_add_f32_e32 v68, 1.0, v68
	v_add_f32_e32 v69, 1.0, v69
	v_rcp_f32_e32 v66, v66
	v_rcp_f32_e32 v67, v67
	s_waitcnt vmcnt(1)
	v_lshlrev_b32_e32 v121, 16, v126
	v_and_b32_e32 v122, 0xffff0000, v126
	v_lshlrev_b32_e32 v123, 16, v127
	v_and_b32_e32 v124, 0xffff0000, v127
	v_lshlrev_b32_e32 v125, 16, v128
	v_and_b32_e32 v126, 0xffff0000, v128
	v_lshlrev_b32_e32 v127, 16, v129
	v_and_b32_e32 v128, 0xffff0000, v129
	v_mul_f32_e32 v1, v1, v121
	v_mul_f32_e32 v121, v114, v125
	v_mul_f32_e32 v114, v118, v122
	v_mul_f32_e32 v118, v115, v126
	v_mul_f32_e32 v115, v119, v123
	v_mul_f32_e32 v119, v116, v127
	v_mul_f32_e32 v116, v120, v124
	v_mul_f32_e32 v117, v117, v128
	v_cvt_pk_bf16_f32 v114, v1, v114
	v_cvt_pk_bf16_f32 v115, v115, v116
	v_cvt_pk_bf16_f32 v116, v121, v118
	v_cvt_pk_bf16_f32 v117, v119, v117
	global_load_dwordx4 v[118:121], v[134:135], off
	v_add_f32_e32 v1, v110, v78
	v_add_f32_e32 v110, v111, v79
	v_add_f32_e32 v111, v112, v80
	v_add_f32_e32 v112, v113, v81
	v_mul_f32_e32 v1, 0xbfb8aa3b, v1
	v_mul_f32_e32 v110, 0xbfb8aa3b, v110
	v_mul_f32_e32 v111, 0xbfb8aa3b, v111
	v_mul_f32_e32 v112, 0xbfb8aa3b, v112
	v_exp_f32_e32 v1, v1
	v_exp_f32_e32 v110, v110
	v_exp_f32_e32 v111, v111
	v_exp_f32_e32 v112, v112
	v_add_f32_e32 v1, 1.0, v1
	v_add_f32_e32 v110, 1.0, v110
	v_add_f32_e32 v111, 1.0, v111
	v_add_f32_e32 v112, 1.0, v112
	v_rcp_f32_e32 v1, v1
	v_rcp_f32_e32 v110, v110
	v_rcp_f32_e32 v111, v111
	v_rcp_f32_e32 v112, v112
	global_store_dwordx4 v[132:133], v[114:117], off offset:1280
	v_rcp_f32_e32 v68, v68
	v_rcp_f32_e32 v69, v69
	v_add_f32_e32 v50, v50, v58
	v_add_f32_e32 v51, v51, v59
	v_add_f32_e32 v52, v52, v60
	v_add_f32_e32 v53, v53, v61
	v_mul_f32_e32 v50, 0xbfb8aa3b, v50
	v_mul_f32_e32 v51, 0xbfb8aa3b, v51
	v_mul_f32_e32 v52, 0xbfb8aa3b, v52
	v_mul_f32_e32 v53, 0xbfb8aa3b, v53
	v_exp_f32_e32 v50, v50
	v_exp_f32_e32 v51, v51
	v_exp_f32_e32 v52, v52
	v_exp_f32_e32 v53, v53
	v_add_f32_e32 v50, 1.0, v50
	v_add_f32_e32 v51, 1.0, v51
	v_add_f32_e32 v52, 1.0, v52
	v_add_f32_e32 v53, 1.0, v53
	v_rcp_f32_e32 v50, v50
	v_rcp_f32_e32 v51, v51
	v_rcp_f32_e32 v52, v52
	v_rcp_f32_e32 v53, v53
	v_add_f32_e32 v42, v42, v74
	v_add_f32_e32 v43, v43, v75
	v_add_f32_e32 v44, v44, v76
	v_add_f32_e32 v45, v45, v77
	v_mul_f32_e32 v42, 0xbfb8aa3b, v42
	v_mul_f32_e32 v43, 0xbfb8aa3b, v43
	v_mul_f32_e32 v44, 0xbfb8aa3b, v44
	v_mul_f32_e32 v45, 0xbfb8aa3b, v45
	v_exp_f32_e32 v42, v42
	v_exp_f32_e32 v43, v43
	v_exp_f32_e32 v44, v44
	v_exp_f32_e32 v45, v45
	v_add_f32_e32 v42, 1.0, v42
	v_add_f32_e32 v43, 1.0, v43
	v_add_f32_e32 v44, 1.0, v44
	v_add_f32_e32 v45, 1.0, v45
	v_rcp_f32_e32 v42, v42
	v_rcp_f32_e32 v43, v43
	v_rcp_f32_e32 v44, v44
	v_rcp_f32_e32 v45, v45
	v_add_f32_e32 v34, v34, v58
	v_add_f32_e32 v35, v35, v59
	v_add_f32_e32 v36, v36, v60
	v_add_f32_e32 v37, v37, v61
	v_mul_f32_e32 v34, 0xbfb8aa3b, v34
	v_mul_f32_e32 v35, 0xbfb8aa3b, v35
	v_mul_f32_e32 v36, 0xbfb8aa3b, v36
	v_mul_f32_e32 v37, 0xbfb8aa3b, v37
	v_exp_f32_e32 v34, v34
	v_exp_f32_e32 v35, v35
	v_exp_f32_e32 v36, v36
	v_exp_f32_e32 v37, v37
	v_add_f32_e32 v34, 1.0, v34
	v_add_f32_e32 v35, 1.0, v35
	v_add_f32_e32 v36, 1.0, v36
	v_add_f32_e32 v37, 1.0, v37
	s_waitcnt vmcnt(1)
	v_lshlrev_b32_e32 v113, 16, v118
	v_and_b32_e32 v114, 0xffff0000, v118
	v_lshlrev_b32_e32 v115, 16, v119
	v_and_b32_e32 v116, 0xffff0000, v119
	v_lshlrev_b32_e32 v117, 16, v120
	v_and_b32_e32 v118, 0xffff0000, v120
	v_lshlrev_b32_e32 v119, 16, v121
	v_and_b32_e32 v120, 0xffff0000, v121
	v_mul_f32_e32 v1, v1, v113
	v_mul_f32_e32 v113, v106, v117
	v_mul_f32_e32 v106, v110, v114
	v_mul_f32_e32 v110, v107, v118
	v_mul_f32_e32 v107, v111, v115
	v_mul_f32_e32 v111, v108, v119
	v_mul_f32_e32 v108, v112, v116
	v_mul_f32_e32 v109, v109, v120
	v_cvt_pk_bf16_f32 v106, v1, v106
	v_cvt_pk_bf16_f32 v107, v107, v108
	v_cvt_pk_bf16_f32 v108, v113, v110
	v_cvt_pk_bf16_f32 v109, v111, v109
	global_load_dwordx4 v[110:113], v[134:135], off offset:256
	v_add_f32_e32 v1, v102, v62
	v_add_f32_e32 v102, v103, v63
	v_add_f32_e32 v103, v104, v64
	v_add_f32_e32 v104, v105, v65
	v_mul_f32_e32 v1, 0xbfb8aa3b, v1
	v_mul_f32_e32 v102, 0xbfb8aa3b, v102
	v_mul_f32_e32 v103, 0xbfb8aa3b, v103
	v_mul_f32_e32 v104, 0xbfb8aa3b, v104
	v_exp_f32_e32 v1, v1
	v_exp_f32_e32 v102, v102
	v_exp_f32_e32 v103, v103
	v_exp_f32_e32 v104, v104
	v_add_f32_e32 v1, 1.0, v1
	v_add_f32_e32 v102, 1.0, v102
	v_add_f32_e32 v103, 1.0, v103
	v_add_f32_e32 v104, 1.0, v104
	v_add_u32_e32 v114, 0xffff15a0, v148
	v_lshlrev_b64 v[116:117], 11, v[130:131]
	v_rcp_f32_e32 v1, v1
	v_rcp_f32_e32 v102, v102
	v_rcp_f32_e32 v103, v103
	v_rcp_f32_e32 v104, v104
	v_ashrrev_i32_e32 v115, 31, v114
	v_lshl_add_u64 v[116:117], s[60:61], 0, v[116:117]
	v_lshlrev_b64 v[118:119], 10, v[114:115]
	v_lshl_add_u64 v[116:117], v[116:117], 0, v[146:147]
	v_lshl_add_u64 v[118:119], s[80:81], 0, v[118:119]
	global_store_dwordx4 v[116:117], v[106:109], off offset:1024
	v_lshl_add_u64 v[118:119], v[118:119], 0, v[146:147]
	v_rcp_f32_e32 v34, v34
	v_rcp_f32_e32 v35, v35
	v_rcp_f32_e32 v36, v36
	v_rcp_f32_e32 v37, v37
	v_add_f32_e32 v26, v26, v74
	v_add_f32_e32 v27, v27, v75
	v_add_f32_e32 v28, v28, v76
	v_add_f32_e32 v29, v29, v77
	v_mul_f32_e32 v26, 0xbfb8aa3b, v26
	v_mul_f32_e32 v27, 0xbfb8aa3b, v27
	v_mul_f32_e32 v28, 0xbfb8aa3b, v28
	v_mul_f32_e32 v29, 0xbfb8aa3b, v29
	v_exp_f32_e32 v26, v26
	v_exp_f32_e32 v27, v27
	v_exp_f32_e32 v28, v28
	v_exp_f32_e32 v29, v29
	v_add_f32_e32 v26, 1.0, v26
	v_add_f32_e32 v27, 1.0, v27
	v_add_f32_e32 v28, 1.0, v28
	v_add_f32_e32 v29, 1.0, v29
	v_rcp_f32_e32 v26, v26
	v_rcp_f32_e32 v27, v27
	v_rcp_f32_e32 v28, v28
	v_rcp_f32_e32 v29, v29
	v_add_f32_e32 v18, v18, v58
	v_add_f32_e32 v19, v19, v59
	v_add_f32_e32 v20, v20, v60
	v_add_f32_e32 v21, v21, v61
	v_mul_f32_e32 v18, 0xbfb8aa3b, v18
	v_mul_f32_e32 v19, 0xbfb8aa3b, v19
	v_mul_f32_e32 v20, 0xbfb8aa3b, v20
	v_mul_f32_e32 v21, 0xbfb8aa3b, v21
	v_exp_f32_e32 v18, v18
	v_exp_f32_e32 v19, v19
	v_exp_f32_e32 v20, v20
	v_exp_f32_e32 v21, v21
	v_add_f32_e32 v18, 1.0, v18
	v_add_f32_e32 v19, 1.0, v19
	v_add_f32_e32 v20, 1.0, v20
	v_add_f32_e32 v21, 1.0, v21
	v_rcp_f32_e32 v18, v18
	v_rcp_f32_e32 v19, v19
	v_rcp_f32_e32 v20, v20
	v_rcp_f32_e32 v21, v21
	v_add_f32_e32 v10, v10, v74
	v_add_f32_e32 v11, v11, v75
	v_add_f32_e32 v12, v12, v76
	v_add_f32_e32 v13, v13, v77
	v_mul_f32_e32 v10, 0xbfb8aa3b, v10
	v_mul_f32_e32 v11, 0xbfb8aa3b, v11
	s_waitcnt vmcnt(1)
	v_lshlrev_b32_e32 v105, 16, v110
	v_and_b32_e32 v106, 0xffff0000, v110
	v_lshlrev_b32_e32 v107, 16, v111
	v_and_b32_e32 v108, 0xffff0000, v111
	v_lshlrev_b32_e32 v109, 16, v112
	v_and_b32_e32 v110, 0xffff0000, v112
	v_lshlrev_b32_e32 v111, 16, v113
	v_and_b32_e32 v112, 0xffff0000, v113
	v_mul_f32_e32 v1, v1, v105
	v_mul_f32_e32 v105, v98, v109
	v_mul_f32_e32 v98, v102, v106
	v_mul_f32_e32 v102, v99, v110
	v_mul_f32_e32 v99, v103, v107
	v_mul_f32_e32 v103, v100, v111
	v_mul_f32_e32 v100, v104, v108
	v_mul_f32_e32 v101, v101, v112
	v_cvt_pk_bf16_f32 v98, v1, v98
	v_cvt_pk_bf16_f32 v99, v99, v100
	v_cvt_pk_bf16_f32 v100, v105, v102
	v_cvt_pk_bf16_f32 v101, v103, v101
	global_load_dwordx4 v[102:105], v[118:119], off
	v_add_f32_e32 v1, v94, v78
	v_add_f32_e32 v94, v95, v79
	v_add_f32_e32 v95, v96, v80
	v_add_f32_e32 v96, v97, v81
	v_mul_f32_e32 v1, 0xbfb8aa3b, v1
	v_mul_f32_e32 v94, 0xbfb8aa3b, v94
	v_mul_f32_e32 v95, 0xbfb8aa3b, v95
	v_mul_f32_e32 v96, 0xbfb8aa3b, v96
	v_exp_f32_e32 v1, v1
	v_exp_f32_e32 v94, v94
	v_exp_f32_e32 v95, v95
	v_exp_f32_e32 v96, v96
	v_add_f32_e32 v1, 1.0, v1
	v_add_f32_e32 v94, 1.0, v94
	v_add_f32_e32 v95, 1.0, v95
	v_add_f32_e32 v96, 1.0, v96
	v_rcp_f32_e32 v1, v1
	v_rcp_f32_e32 v94, v94
	v_rcp_f32_e32 v95, v95
	v_rcp_f32_e32 v96, v96
	global_store_dwordx4 v[116:117], v[98:101], off offset:1280
	v_mul_f32_e32 v12, 0xbfb8aa3b, v12
	v_mul_f32_e32 v13, 0xbfb8aa3b, v13
	v_exp_f32_e32 v10, v10
	v_exp_f32_e32 v11, v11
	v_exp_f32_e32 v12, v12
	v_exp_f32_e32 v13, v13
	v_add_f32_e32 v10, 1.0, v10
	v_add_f32_e32 v11, 1.0, v11
	v_add_f32_e32 v12, 1.0, v12
	v_add_f32_e32 v13, 1.0, v13
	v_rcp_f32_e32 v10, v10
	v_rcp_f32_e32 v11, v11
	v_rcp_f32_e32 v12, v12
	v_rcp_f32_e32 v13, v13
	v_add_f32_e32 v2, v2, v58
	v_add_f32_e32 v3, v3, v59
	v_add_f32_e32 v4, v4, v60
	v_add_f32_e32 v5, v5, v61
	v_mul_f32_e32 v2, 0xbfb8aa3b, v2
	v_mul_f32_e32 v3, 0xbfb8aa3b, v3
	v_mul_f32_e32 v4, 0xbfb8aa3b, v4
	v_mul_f32_e32 v5, 0xbfb8aa3b, v5
	v_exp_f32_e32 v2, v2
	v_exp_f32_e32 v3, v3
	v_exp_f32_e32 v4, v4
	v_exp_f32_e32 v5, v5
	v_add_f32_e32 v2, 1.0, v2
	v_add_f32_e32 v3, 1.0, v3
	v_add_f32_e32 v4, 1.0, v4
	v_add_f32_e32 v5, 1.0, v5
	v_rcp_f32_e32 v2, v2
	v_rcp_f32_e32 v3, v3
	v_rcp_f32_e32 v4, v4
	v_rcp_f32_e32 v5, v5
	s_waitcnt vmcnt(1)
	v_lshlrev_b32_e32 v97, 16, v102
	v_and_b32_e32 v98, 0xffff0000, v102
	v_lshlrev_b32_e32 v99, 16, v103
	v_and_b32_e32 v100, 0xffff0000, v103
	v_lshlrev_b32_e32 v101, 16, v104
	v_and_b32_e32 v102, 0xffff0000, v104
	v_lshlrev_b32_e32 v103, 16, v105
	v_and_b32_e32 v104, 0xffff0000, v105
	v_mul_f32_e32 v1, v1, v97
	v_mul_f32_e32 v97, v90, v101
	v_mul_f32_e32 v90, v94, v98
	v_mul_f32_e32 v94, v91, v102
	v_mul_f32_e32 v91, v95, v99
	v_mul_f32_e32 v95, v92, v103
	v_mul_f32_e32 v92, v96, v100
	v_mul_f32_e32 v93, v93, v104
	v_cvt_pk_bf16_f32 v90, v1, v90
	v_cvt_pk_bf16_f32 v91, v91, v92
	v_cvt_pk_bf16_f32 v92, v97, v94
	v_cvt_pk_bf16_f32 v93, v95, v93
	global_load_dwordx4 v[94:97], v[118:119], off offset:256
	v_add_f32_e32 v1, v86, v62
	v_add_f32_e32 v86, v87, v63
	v_add_f32_e32 v87, v88, v64
	v_add_f32_e32 v88, v89, v65
	v_mul_f32_e32 v1, 0xbfb8aa3b, v1
	v_mul_f32_e32 v86, 0xbfb8aa3b, v86
	v_mul_f32_e32 v87, 0xbfb8aa3b, v87
	v_mul_f32_e32 v88, 0xbfb8aa3b, v88
	v_exp_f32_e32 v1, v1
	v_exp_f32_e32 v86, v86
	v_exp_f32_e32 v87, v87
	v_exp_f32_e32 v88, v88
	v_add_f32_e32 v1, 1.0, v1
	v_add_f32_e32 v86, 1.0, v86
	v_add_f32_e32 v87, 1.0, v87
	v_add_f32_e32 v88, 1.0, v88
	v_add_u32_e32 v98, 0x60, v148
	v_lshlrev_b64 v[100:101], 11, v[114:115]
	v_rcp_f32_e32 v1, v1
	v_rcp_f32_e32 v86, v86
	v_rcp_f32_e32 v87, v87
	v_rcp_f32_e32 v88, v88
	v_ashrrev_i32_e32 v99, 31, v98
	v_lshl_add_u64 v[100:101], s[60:61], 0, v[100:101]
	v_lshlrev_b64 v[102:103], 10, v[98:99]
	v_lshl_add_u64 v[100:101], v[100:101], 0, v[146:147]
	v_lshl_add_u64 v[102:103], s[80:81], 0, v[102:103]
	global_store_dwordx4 v[100:101], v[90:93], off offset:1024
	v_lshl_add_u64 v[102:103], v[102:103], 0, v[146:147]
	s_waitcnt vmcnt(1)
	v_lshlrev_b32_e32 v89, 16, v94
	v_and_b32_e32 v90, 0xffff0000, v94
	v_lshlrev_b32_e32 v91, 16, v95
	v_and_b32_e32 v92, 0xffff0000, v95
	v_lshlrev_b32_e32 v93, 16, v96
	v_and_b32_e32 v94, 0xffff0000, v96
	v_lshlrev_b32_e32 v95, 16, v97
	v_and_b32_e32 v96, 0xffff0000, v97
	v_mul_f32_e32 v1, v1, v89
	v_mul_f32_e32 v89, v82, v93
	v_mul_f32_e32 v82, v86, v90
	v_mul_f32_e32 v86, v83, v94
	v_mul_f32_e32 v83, v87, v91
	v_mul_f32_e32 v87, v84, v95
	v_mul_f32_e32 v84, v88, v92
	v_mul_f32_e32 v85, v85, v96
	v_cvt_pk_bf16_f32 v82, v1, v82
	v_cvt_pk_bf16_f32 v83, v83, v84
	v_cvt_pk_bf16_f32 v84, v89, v86
	v_cvt_pk_bf16_f32 v85, v87, v85
	global_load_dwordx4 v[86:89], v[102:103], off
	v_add_f32_e32 v1, v70, v78
	v_add_f32_e32 v70, v71, v79
	v_add_f32_e32 v71, v72, v80
	v_add_f32_e32 v72, v73, v81
	v_mul_f32_e32 v1, 0xbfb8aa3b, v1
	v_mul_f32_e32 v70, 0xbfb8aa3b, v70
	v_mul_f32_e32 v71, 0xbfb8aa3b, v71
	v_mul_f32_e32 v72, 0xbfb8aa3b, v72
	v_exp_f32_e32 v1, v1
	v_exp_f32_e32 v70, v70
	v_exp_f32_e32 v71, v71
	v_exp_f32_e32 v72, v72
	v_add_f32_e32 v1, 1.0, v1
	v_add_f32_e32 v70, 1.0, v70
	v_add_f32_e32 v71, 1.0, v71
	v_add_f32_e32 v72, 1.0, v72
	v_rcp_f32_e32 v1, v1
	v_rcp_f32_e32 v70, v70
	v_rcp_f32_e32 v71, v71
	v_rcp_f32_e32 v72, v72
	global_store_dwordx4 v[100:101], v[82:85], off offset:1280
	s_waitcnt vmcnt(1)
	v_lshlrev_b32_e32 v73, 16, v86
	v_and_b32_e32 v82, 0xffff0000, v86
	v_lshlrev_b32_e32 v83, 16, v87
	v_and_b32_e32 v84, 0xffff0000, v87
	v_lshlrev_b32_e32 v85, 16, v88
	v_and_b32_e32 v86, 0xffff0000, v88
	v_lshlrev_b32_e32 v87, 16, v89
	v_and_b32_e32 v88, 0xffff0000, v89
	v_mul_f32_e32 v1, v1, v73
	v_mul_f32_e32 v73, v66, v85
	v_mul_f32_e32 v66, v70, v82
	v_mul_f32_e32 v70, v67, v86
	v_mul_f32_e32 v67, v71, v83
	v_mul_f32_e32 v71, v68, v87
	v_mul_f32_e32 v68, v72, v84
	v_mul_f32_e32 v69, v69, v88
	v_cvt_pk_bf16_f32 v66, v1, v66
	v_cvt_pk_bf16_f32 v67, v67, v68
	v_cvt_pk_bf16_f32 v68, v73, v70
	v_cvt_pk_bf16_f32 v69, v71, v69
	global_load_dwordx4 v[70:73], v[102:103], off offset:256
	v_add_f32_e32 v1, v54, v62
	v_add_f32_e32 v54, v55, v63
	v_add_f32_e32 v55, v56, v64
	v_add_f32_e32 v56, v57, v65
	v_mul_f32_e32 v1, 0xbfb8aa3b, v1
	v_mul_f32_e32 v54, 0xbfb8aa3b, v54
	v_mul_f32_e32 v55, 0xbfb8aa3b, v55
	v_mul_f32_e32 v56, 0xbfb8aa3b, v56
	v_exp_f32_e32 v1, v1
	v_exp_f32_e32 v54, v54
	v_exp_f32_e32 v55, v55
	v_exp_f32_e32 v56, v56
	v_add_f32_e32 v1, 1.0, v1
	v_add_f32_e32 v54, 1.0, v54
	v_add_f32_e32 v55, 1.0, v55
	v_add_f32_e32 v56, 1.0, v56
	v_add_u32_e32 v82, 0x70, v148
	v_lshlrev_b64 v[84:85], 11, v[98:99]
	v_rcp_f32_e32 v1, v1
	v_rcp_f32_e32 v54, v54
	v_rcp_f32_e32 v55, v55
	v_rcp_f32_e32 v56, v56
	v_ashrrev_i32_e32 v83, 31, v82
	v_lshl_add_u64 v[84:85], s[60:61], 0, v[84:85]
	v_lshlrev_b64 v[86:87], 10, v[82:83]
	v_lshl_add_u64 v[84:85], v[84:85], 0, v[146:147]
	v_lshl_add_u64 v[86:87], s[80:81], 0, v[86:87]
	global_store_dwordx4 v[84:85], v[66:69], off offset:1024
	v_lshl_add_u64 v[86:87], v[86:87], 0, v[146:147]
	s_waitcnt vmcnt(1)
	v_lshlrev_b32_e32 v57, 16, v70
	v_and_b32_e32 v66, 0xffff0000, v70
	v_lshlrev_b32_e32 v67, 16, v71
	v_and_b32_e32 v68, 0xffff0000, v71
	v_lshlrev_b32_e32 v69, 16, v72
	v_and_b32_e32 v70, 0xffff0000, v72
	v_lshlrev_b32_e32 v71, 16, v73
	v_and_b32_e32 v72, 0xffff0000, v73
	v_mul_f32_e32 v1, v1, v57
	v_mul_f32_e32 v57, v50, v69
	v_mul_f32_e32 v50, v54, v66
	v_mul_f32_e32 v54, v51, v70
	v_mul_f32_e32 v51, v55, v67
	v_mul_f32_e32 v55, v52, v71
	v_mul_f32_e32 v52, v56, v68
	v_mul_f32_e32 v53, v53, v72
	v_cvt_pk_bf16_f32 v50, v1, v50
	v_cvt_pk_bf16_f32 v51, v51, v52
	v_cvt_pk_bf16_f32 v52, v57, v54
	v_cvt_pk_bf16_f32 v53, v55, v53
	global_load_dwordx4 v[54:57], v[86:87], off
	v_add_f32_e32 v1, v46, v78
	v_add_f32_e32 v46, v47, v79
	v_add_f32_e32 v47, v48, v80
	v_add_f32_e32 v48, v49, v81
	v_mul_f32_e32 v1, 0xbfb8aa3b, v1
	v_mul_f32_e32 v46, 0xbfb8aa3b, v46
	v_mul_f32_e32 v47, 0xbfb8aa3b, v47
	v_mul_f32_e32 v48, 0xbfb8aa3b, v48
	v_exp_f32_e32 v1, v1
	v_exp_f32_e32 v46, v46
	v_exp_f32_e32 v47, v47
	v_exp_f32_e32 v48, v48
	v_add_f32_e32 v1, 1.0, v1
	v_add_f32_e32 v46, 1.0, v46
	v_add_f32_e32 v47, 1.0, v47
	v_add_f32_e32 v48, 1.0, v48
	v_rcp_f32_e32 v1, v1
	v_rcp_f32_e32 v46, v46
	v_rcp_f32_e32 v47, v47
	v_rcp_f32_e32 v48, v48
	global_store_dwordx4 v[84:85], v[50:53], off offset:1280
	s_waitcnt vmcnt(1)
	v_lshlrev_b32_e32 v49, 16, v54
	v_and_b32_e32 v50, 0xffff0000, v54
	v_lshlrev_b32_e32 v51, 16, v55
	v_and_b32_e32 v52, 0xffff0000, v55
	v_lshlrev_b32_e32 v53, 16, v56
	v_and_b32_e32 v54, 0xffff0000, v56
	v_lshlrev_b32_e32 v55, 16, v57
	v_and_b32_e32 v56, 0xffff0000, v57
	v_mul_f32_e32 v1, v1, v49
	v_mul_f32_e32 v49, v42, v53
	v_mul_f32_e32 v42, v46, v50
	v_mul_f32_e32 v46, v43, v54
	v_mul_f32_e32 v43, v47, v51
	v_mul_f32_e32 v47, v44, v55
	v_mul_f32_e32 v44, v48, v52
	v_mul_f32_e32 v45, v45, v56
	v_cvt_pk_bf16_f32 v42, v1, v42
	v_cvt_pk_bf16_f32 v43, v43, v44
	v_cvt_pk_bf16_f32 v44, v49, v46
	v_cvt_pk_bf16_f32 v45, v47, v45
	global_load_dwordx4 v[46:49], v[86:87], off offset:256
	v_add_f32_e32 v1, v38, v62
	v_add_f32_e32 v38, v39, v63
	v_add_f32_e32 v39, v40, v64
	v_add_f32_e32 v40, v41, v65
	v_mul_f32_e32 v1, 0xbfb8aa3b, v1
	v_mul_f32_e32 v38, 0xbfb8aa3b, v38
	v_mul_f32_e32 v39, 0xbfb8aa3b, v39
	v_mul_f32_e32 v40, 0xbfb8aa3b, v40
	v_exp_f32_e32 v1, v1
	v_exp_f32_e32 v38, v38
	v_exp_f32_e32 v39, v39
	v_exp_f32_e32 v40, v40
	v_add_f32_e32 v1, 1.0, v1
	v_add_f32_e32 v38, 1.0, v38
	v_add_f32_e32 v39, 1.0, v39
	v_add_f32_e32 v40, 1.0, v40
	v_add_u32_e32 v50, 0x80, v148
	v_lshlrev_b64 v[52:53], 11, v[82:83]
	v_rcp_f32_e32 v1, v1
	v_rcp_f32_e32 v38, v38
	v_rcp_f32_e32 v39, v39
	v_rcp_f32_e32 v40, v40
	v_ashrrev_i32_e32 v51, 31, v50
	v_lshl_add_u64 v[52:53], s[60:61], 0, v[52:53]
	v_lshlrev_b64 v[54:55], 10, v[50:51]
	v_lshl_add_u64 v[52:53], v[52:53], 0, v[146:147]
	v_lshl_add_u64 v[54:55], s[80:81], 0, v[54:55]
	global_store_dwordx4 v[52:53], v[42:45], off offset:1024
	v_lshl_add_u64 v[54:55], v[54:55], 0, v[146:147]
	s_waitcnt vmcnt(1)
	v_lshlrev_b32_e32 v41, 16, v46
	v_and_b32_e32 v42, 0xffff0000, v46
	v_lshlrev_b32_e32 v43, 16, v47
	v_and_b32_e32 v44, 0xffff0000, v47
	v_lshlrev_b32_e32 v45, 16, v48
	v_and_b32_e32 v46, 0xffff0000, v48
	v_lshlrev_b32_e32 v47, 16, v49
	v_and_b32_e32 v48, 0xffff0000, v49
	v_mul_f32_e32 v1, v1, v41
	v_mul_f32_e32 v41, v34, v45
	v_mul_f32_e32 v34, v38, v42
	v_mul_f32_e32 v38, v35, v46
	v_mul_f32_e32 v35, v39, v43
	v_mul_f32_e32 v39, v36, v47
	v_mul_f32_e32 v36, v40, v44
	v_mul_f32_e32 v37, v37, v48
	v_cvt_pk_bf16_f32 v34, v1, v34
	v_cvt_pk_bf16_f32 v35, v35, v36
	v_cvt_pk_bf16_f32 v36, v41, v38
	v_cvt_pk_bf16_f32 v37, v39, v37
	global_load_dwordx4 v[38:41], v[54:55], off
	v_add_f32_e32 v1, v30, v78
	v_add_f32_e32 v30, v31, v79
	v_add_f32_e32 v31, v32, v80
	v_add_f32_e32 v32, v33, v81
	v_mul_f32_e32 v1, 0xbfb8aa3b, v1
	v_mul_f32_e32 v30, 0xbfb8aa3b, v30
	v_mul_f32_e32 v31, 0xbfb8aa3b, v31
	v_mul_f32_e32 v32, 0xbfb8aa3b, v32
	v_exp_f32_e32 v1, v1
	v_exp_f32_e32 v30, v30
	v_exp_f32_e32 v31, v31
	v_exp_f32_e32 v32, v32
	v_add_f32_e32 v1, 1.0, v1
	v_add_f32_e32 v30, 1.0, v30
	v_add_f32_e32 v31, 1.0, v31
	v_add_f32_e32 v32, 1.0, v32
	v_rcp_f32_e32 v1, v1
	v_rcp_f32_e32 v30, v30
	v_rcp_f32_e32 v31, v31
	v_rcp_f32_e32 v32, v32
	global_store_dwordx4 v[52:53], v[34:37], off offset:1280
	s_waitcnt vmcnt(1)
	v_lshlrev_b32_e32 v33, 16, v38
	v_and_b32_e32 v34, 0xffff0000, v38
	v_lshlrev_b32_e32 v35, 16, v39
	v_and_b32_e32 v36, 0xffff0000, v39
	v_lshlrev_b32_e32 v37, 16, v40
	v_and_b32_e32 v38, 0xffff0000, v40
	v_lshlrev_b32_e32 v39, 16, v41
	v_and_b32_e32 v40, 0xffff0000, v41
	v_mul_f32_e32 v1, v1, v33
	v_mul_f32_e32 v33, v26, v37
	v_mul_f32_e32 v26, v30, v34
	v_mul_f32_e32 v30, v27, v38
	v_mul_f32_e32 v27, v31, v35
	v_mul_f32_e32 v31, v28, v39
	v_mul_f32_e32 v28, v32, v36
	v_mul_f32_e32 v29, v29, v40
	v_cvt_pk_bf16_f32 v26, v1, v26
	v_cvt_pk_bf16_f32 v27, v27, v28
	v_cvt_pk_bf16_f32 v28, v33, v30
	v_cvt_pk_bf16_f32 v29, v31, v29
	global_load_dwordx4 v[30:33], v[54:55], off offset:256
	v_add_f32_e32 v1, v22, v62
	v_add_f32_e32 v22, v23, v63
	v_add_f32_e32 v23, v24, v64
	v_add_f32_e32 v24, v25, v65
	v_mul_f32_e32 v1, 0xbfb8aa3b, v1
	v_mul_f32_e32 v22, 0xbfb8aa3b, v22
	v_mul_f32_e32 v23, 0xbfb8aa3b, v23
	v_mul_f32_e32 v24, 0xbfb8aa3b, v24
	v_exp_f32_e32 v1, v1
	v_exp_f32_e32 v22, v22
	v_exp_f32_e32 v23, v23
	v_exp_f32_e32 v24, v24
	v_add_f32_e32 v1, 1.0, v1
	v_add_f32_e32 v22, 1.0, v22
	v_add_f32_e32 v23, 1.0, v23
	v_add_f32_e32 v24, 1.0, v24
	v_add_u32_e32 v34, 0xffff15a0, v148
	v_lshlrev_b64 v[36:37], 11, v[50:51]
	v_rcp_f32_e32 v1, v1
	v_rcp_f32_e32 v22, v22
	v_rcp_f32_e32 v23, v23
	v_rcp_f32_e32 v24, v24
	v_ashrrev_i32_e32 v35, 31, v34
	v_lshl_add_u64 v[36:37], s[60:61], 0, v[36:37]
	v_lshlrev_b64 v[38:39], 10, v[34:35]
	v_lshl_add_u64 v[36:37], v[36:37], 0, v[146:147]
	v_lshl_add_u64 v[38:39], s[80:81], 0, v[38:39]
	global_store_dwordx4 v[36:37], v[26:29], off offset:1024
	v_lshl_add_u64 v[38:39], v[38:39], 0, v[146:147]
	s_waitcnt vmcnt(1)
	v_lshlrev_b32_e32 v25, 16, v30
	v_and_b32_e32 v26, 0xffff0000, v30
	v_lshlrev_b32_e32 v27, 16, v31
	v_and_b32_e32 v28, 0xffff0000, v31
	v_lshlrev_b32_e32 v29, 16, v32
	v_and_b32_e32 v30, 0xffff0000, v32
	v_lshlrev_b32_e32 v31, 16, v33
	v_and_b32_e32 v32, 0xffff0000, v33
	v_mul_f32_e32 v1, v1, v25
	v_mul_f32_e32 v25, v18, v29
	v_mul_f32_e32 v18, v22, v26
	v_mul_f32_e32 v22, v19, v30
	v_mul_f32_e32 v19, v23, v27
	v_mul_f32_e32 v23, v20, v31
	v_mul_f32_e32 v20, v24, v28
	v_mul_f32_e32 v21, v21, v32
	v_cvt_pk_bf16_f32 v18, v1, v18
	v_cvt_pk_bf16_f32 v19, v19, v20
	v_cvt_pk_bf16_f32 v20, v25, v22
	v_cvt_pk_bf16_f32 v21, v23, v21
	global_load_dwordx4 v[22:25], v[38:39], off
	v_add_f32_e32 v1, v14, v78
	v_add_f32_e32 v14, v15, v79
	v_add_f32_e32 v15, v16, v80
	v_add_f32_e32 v16, v17, v81
	v_mul_f32_e32 v1, 0xbfb8aa3b, v1
	v_mul_f32_e32 v14, 0xbfb8aa3b, v14
	v_mul_f32_e32 v15, 0xbfb8aa3b, v15
	v_mul_f32_e32 v16, 0xbfb8aa3b, v16
	v_exp_f32_e32 v1, v1
	v_exp_f32_e32 v14, v14
	v_exp_f32_e32 v15, v15
	v_exp_f32_e32 v16, v16
	v_add_f32_e32 v1, 1.0, v1
	v_add_f32_e32 v14, 1.0, v14
	v_add_f32_e32 v15, 1.0, v15
	v_add_f32_e32 v16, 1.0, v16
	v_rcp_f32_e32 v1, v1
	v_rcp_f32_e32 v14, v14
	v_rcp_f32_e32 v15, v15
	v_rcp_f32_e32 v16, v16
	global_store_dwordx4 v[36:37], v[18:21], off offset:1280
	s_waitcnt vmcnt(1)
	v_lshlrev_b32_e32 v17, 16, v22
	v_and_b32_e32 v18, 0xffff0000, v22
	v_lshlrev_b32_e32 v19, 16, v23
	v_and_b32_e32 v20, 0xffff0000, v23
	v_lshlrev_b32_e32 v21, 16, v24
	v_and_b32_e32 v22, 0xffff0000, v24
	v_lshlrev_b32_e32 v23, 16, v25
	v_and_b32_e32 v24, 0xffff0000, v25
	v_mul_f32_e32 v1, v1, v17
	v_mul_f32_e32 v17, v10, v21
	v_mul_f32_e32 v10, v14, v18
	v_mul_f32_e32 v14, v11, v22
	v_mul_f32_e32 v11, v15, v19
	v_mul_f32_e32 v15, v12, v23
	v_mul_f32_e32 v12, v16, v20
	v_mul_f32_e32 v13, v13, v24
	v_cvt_pk_bf16_f32 v10, v1, v10
	v_cvt_pk_bf16_f32 v11, v11, v12
	v_cvt_pk_bf16_f32 v12, v17, v14
	v_cvt_pk_bf16_f32 v13, v15, v13
	global_load_dwordx4 v[14:17], v[38:39], off offset:256
	v_add_f32_e32 v1, v6, v62
	v_add_f32_e32 v6, v7, v63
	v_add_f32_e32 v7, v8, v64
	v_add_f32_e32 v8, v9, v65
	v_mul_f32_e32 v1, 0xbfb8aa3b, v1
	v_mul_f32_e32 v6, 0xbfb8aa3b, v6
	v_mul_f32_e32 v7, 0xbfb8aa3b, v7
	v_mul_f32_e32 v8, 0xbfb8aa3b, v8
	v_exp_f32_e32 v1, v1
	v_exp_f32_e32 v6, v6
	v_exp_f32_e32 v7, v7
	v_exp_f32_e32 v8, v8
	v_add_f32_e32 v1, 1.0, v1
	v_add_f32_e32 v6, 1.0, v6
	v_add_f32_e32 v7, 1.0, v7
	v_add_f32_e32 v8, 1.0, v8
	v_lshlrev_b64 v[18:19], 11, v[34:35]
	v_rcp_f32_e32 v1, v1
	v_rcp_f32_e32 v6, v6
	v_rcp_f32_e32 v7, v7
	v_rcp_f32_e32 v8, v8
	v_lshl_add_u64 v[18:19], s[60:61], 0, v[18:19]
	v_lshl_add_u64 v[18:19], v[18:19], 0, v[146:147]
	global_store_dwordx4 v[18:19], v[10:13], off offset:1024
	s_waitcnt vmcnt(1)
	v_lshlrev_b32_e32 v9, 16, v14
	v_and_b32_e32 v10, 0xffff0000, v14
	v_lshlrev_b32_e32 v11, 16, v15
	v_and_b32_e32 v12, 0xffff0000, v15
	v_lshlrev_b32_e32 v13, 16, v16
	v_and_b32_e32 v14, 0xffff0000, v16
	v_lshlrev_b32_e32 v15, 16, v17
	v_and_b32_e32 v16, 0xffff0000, v17
	v_mul_f32_e32 v1, v1, v9
	v_mul_f32_e32 v9, v2, v13
	v_mul_f32_e32 v2, v6, v10
	v_mul_f32_e32 v6, v3, v14
	v_mul_f32_e32 v3, v7, v11
	v_mul_f32_e32 v7, v4, v15
	v_mul_f32_e32 v4, v8, v12
	v_mul_f32_e32 v5, v5, v16
	v_cvt_pk_bf16_f32 v2, v1, v2
	v_cvt_pk_bf16_f32 v3, v3, v4
	v_cvt_pk_bf16_f32 v4, v9, v6
	v_cvt_pk_bf16_f32 v5, v7, v5
	global_store_dwordx4 v[18:19], v[2:5], off offset:1280
	s_waitcnt vmcnt(0)
	s_barrier
.LBB0_386:
	s_cmp_gt_u32 s3, 0x7f
	s_cbranch_scc1 .LBB0_390
	s_bfe_u32 s5, s3, 0x20001
	s_lshl_b32 s0, s5, 2
	v_readlane_b32 s8, v242, 0
	v_mov_b32_e32 v2, v0
	v_mov_b32_e32 v1, s0
	v_readlane_b32 s12, v242, 4
	v_readlane_b32 s13, v242, 5
	s_nop 4
	global_load_dword v3, v1, s[12:13]
	global_load_dword v6, v1, s[12:13] offset:16
	v_readlane_b32 s9, v242, 1
	s_mov_b32 s9, 0xbfb8aa3b
	v_readlane_b32 s10, v242, 2
	v_readlane_b32 s11, v242, 3
	s_mov_b32 s10, 0x42ce8ed0
	s_mov_b32 s11, 0xc2b17218
	v_mov_b32_e32 v7, 0x7f800000
	s_mov_b32 s12, 0x3f2aaaab
	s_mov_b32 s8, 0x3f317218
	v_mov_b32_e32 v8, 0x3ecc95a3
	s_mov_b32 s4, 0x7f800000
	s_mov_b32 s7, 0x33800000
	v_mov_b32_e32 v9, 0x3f2aaada
	s_lshl_b32 s0, s38, 7
	s_lshl_b32 s1, s3, 5
	s_and_b32 s0, s0, 0x80
	s_and_b32 s6, s1, 0xf00
	s_sub_i32 s6, s6, 0x800
	v_readfirstlane_b32 s3, v2
	v_and_b32_e32 v18, 15, v2
	s_add_i32 s1, s6, 0x800
	s_ashr_i32 s3, s3, 6
	s_mov_b32 s63, 0
	s_lshl_b32 s62, s5, 8
	v_mov_b32_e32 v79, 0
	v_and_b32_e32 v78, 48, v2
	v_ashrrev_i32_e32 v26, 4, v2
	v_bfe_u32 v19, v2, 4, 2
	v_and_b32_e32 v1, 63, v2
	v_lshlrev_b32_e32 v84, 4, v18
	v_mov_b32_e32 v85, v79
	s_mov_b64 s[64:65], 0x50000
	v_mov_b32_e32 v46, v79
	v_mov_b32_e32 v47, v79
	v_mov_b32_e32 v48, v79
	v_mov_b32_e32 v49, v79
	v_mov_b32_e32 v42, v79
	v_mov_b32_e32 v43, v79
	v_mov_b32_e32 v44, v79
	v_mov_b32_e32 v45, v79
	v_mov_b32_e32 v38, v79
	v_mov_b32_e32 v39, v79
	v_mov_b32_e32 v40, v79
	v_mov_b32_e32 v41, v79
	v_mov_b32_e32 v34, v79
	v_mov_b32_e32 v35, v79
	v_mov_b32_e32 v36, v79
	v_mov_b32_e32 v37, v79
	v_mov_b32_e32 v27, v79
	v_mov_b32_e32 v28, v79
	v_mov_b32_e32 v29, v79
	v_readlane_b32 s14, v242, 6
	v_readlane_b32 s15, v242, 7
	v_readlane_b32 s16, v242, 8
	v_readlane_b32 s17, v242, 9
	v_readlane_b32 s18, v242, 10
	v_readlane_b32 s19, v242, 11
	v_readlane_b32 s20, v242, 12
	v_readlane_b32 s21, v242, 13
	v_readlane_b32 s22, v242, 14
	v_readlane_b32 s23, v242, 15
	s_waitcnt vmcnt(1)
	v_mul_f32_e32 v4, 0xbfb8aa3b, v3
	v_fma_f32 v10, v3, s9, -v4
	v_rndne_f32_e32 v11, v4
	v_fmac_f32_e32 v10, 0xb2a5705f, v3
	v_sub_f32_e32 v4, v4, v11
	v_add_f32_e32 v4, v4, v10
	v_cvt_i32_f32_e32 v11, v11
	v_exp_f32_e32 v4, v4
	v_cmp_nlt_f32_e32 vcc, s10, v3
	s_waitcnt vmcnt(0)
	v_mul_f32_e32 v5, 0xbfb8aa3b, v6
	v_fma_f32 v12, v6, s9, -v5
	v_ldexp_f32 v4, v4, v11
	v_cndmask_b32_e32 v4, 0, v4, vcc
	v_cmp_ngt_f32_e32 vcc, s11, v3
	v_rndne_f32_e32 v13, v5
	v_fmac_f32_e32 v12, 0xb2a5705f, v6
	v_cndmask_b32_e32 v3, v7, v4, vcc
	v_sub_f32_e32 v5, v5, v13
	v_add_f32_e32 v11, 1.0, v3
	v_add_f32_e32 v10, v5, v12
	v_add_f32_e32 v12, -1.0, v11
	v_frexp_mant_f32_e32 v14, v11
	v_cvt_f64_f32_e32 v[4:5], v11
	v_sub_f32_e32 v15, v12, v11
	v_frexp_exp_i32_f64_e32 v4, v[4:5]
	v_cmp_gt_f32_e32 vcc, s12, v14
	v_sub_f32_e32 v12, v3, v12
	v_add_f32_e32 v5, 1.0, v15
	v_subbrev_co_u32_e32 v4, vcc, 0, v4, vcc
	v_add_f32_e32 v5, v12, v5
	v_sub_u32_e32 v12, 0, v4
	v_cvt_f32_i32_e32 v4, v4
	v_ldexp_f32 v11, v11, v12
	v_ldexp_f32 v5, v5, v12
	v_add_f32_e32 v12, -1.0, v11
	v_add_f32_e32 v14, 1.0, v11
	v_add_f32_e32 v15, 1.0, v12
	v_add_f32_e32 v16, -1.0, v14
	v_sub_f32_e32 v15, v11, v15
	v_sub_f32_e32 v11, v11, v16
	v_mul_f32_e32 v16, 0x3f317218, v4
	v_add_f32_e32 v15, v5, v15
	v_add_f32_e32 v5, v5, v11
	v_fma_f32 v11, v4, s8, -v16
	v_add_f32_e32 v17, v12, v15
	v_add_f32_e32 v20, v14, v5
	v_fmac_f32_e32 v11, 0xb102e308, v4
	v_sub_f32_e32 v4, v12, v17
	v_sub_f32_e32 v12, v14, v20
	v_rcp_f32_e32 v14, v20
	v_add_f32_e32 v21, v16, v11
	v_add_f32_e32 v5, v5, v12
	v_sub_f32_e32 v12, v21, v16
	v_sub_f32_e32 v11, v11, v12
	v_mul_f32_e32 v12, v17, v14
	v_add_f32_e32 v4, v15, v4
	v_mul_f32_e32 v15, v20, v12
	v_fma_f32 v16, v12, v20, -v15
	v_fmac_f32_e32 v16, v12, v5
	v_add_f32_e32 v22, v15, v16
	v_sub_f32_e32 v23, v17, v22
	v_sub_f32_e32 v15, v22, v15
	v_sub_f32_e32 v17, v17, v23
	v_sub_f32_e32 v15, v15, v16
	v_sub_f32_e32 v16, v17, v22
	v_add_f32_e32 v4, v4, v16
	v_add_f32_e32 v4, v15, v4
	v_add_f32_e32 v15, v23, v4
	v_mul_f32_e32 v16, v14, v15
	v_sub_f32_e32 v17, v23, v15
	v_mul_f32_e32 v22, v20, v16
	v_add_f32_e32 v4, v4, v17
	v_add_f32_e32 v17, v12, v16
	v_fma_f32 v20, v16, v20, -v22
	v_sub_f32_e32 v12, v17, v12
	v_fmac_f32_e32 v20, v16, v5
	v_sub_f32_e32 v5, v16, v12
	v_add_f32_e32 v12, v22, v20
	v_sub_f32_e32 v16, v12, v22
	v_sub_f32_e32 v22, v15, v12
	v_sub_f32_e32 v15, v15, v22
	v_sub_f32_e32 v12, v15, v12
	v_sub_f32_e32 v16, v16, v20
	v_add_f32_e32 v4, v4, v12
	v_add_f32_e32 v4, v16, v4
	v_add_f32_e32 v4, v22, v4
	v_mul_f32_e32 v4, v14, v4
	v_add_f32_e32 v4, v5, v4
	v_add_f32_e32 v5, v17, v4
	v_mul_f32_e32 v12, v5, v5
	v_fmamk_f32 v16, v12, 0x3e9b6dac, v8
	v_sub_f32_e32 v14, v5, v17
	v_ldexp_f32 v15, v5, 1
	v_mul_f32_e32 v5, v5, v12
	v_fmaak_f32 v12, v12, v16, 0x3f2aaada
	v_mul_f32_e32 v5, v5, v12
	v_add_f32_e32 v12, v15, v5
	v_sub_f32_e32 v4, v4, v14
	v_sub_f32_e32 v14, v12, v15
	v_ldexp_f32 v4, v4, 1
	v_sub_f32_e32 v5, v5, v14
	v_add_f32_e32 v4, v4, v5
	v_add_f32_e32 v5, v12, v4
	v_sub_f32_e32 v12, v5, v12
	v_add_f32_e32 v14, v21, v5
	v_sub_f32_e32 v4, v4, v12
	v_sub_f32_e32 v12, v14, v21
	v_sub_f32_e32 v15, v14, v12
	v_sub_f32_e32 v5, v5, v12
	v_add_f32_e32 v12, v11, v4
	v_sub_f32_e32 v15, v21, v15
	v_sub_f32_e32 v16, v12, v11
	v_add_f32_e32 v5, v5, v15
	v_sub_f32_e32 v15, v12, v16
	v_sub_f32_e32 v4, v4, v16
	v_sub_f32_e32 v11, v11, v15
	v_add_f32_e32 v5, v12, v5
	v_add_f32_e32 v4, v4, v11
	v_add_f32_e32 v11, v14, v5
	v_sub_f32_e32 v12, v11, v14
	v_sub_f32_e32 v5, v5, v12
	v_add_f32_e32 v4, v4, v5
	v_exp_f32_e32 v5, v10
	v_cvt_i32_f32_e32 v10, v13
	v_add_f32_e32 v4, v11, v4
	v_cmp_neq_f32_e32 vcc, s4, v3
	v_lshlrev_b32_e32 v20, 3, v19
	v_lshlrev_b32_e32 v21, 3, v2
	v_cndmask_b32_e32 v4, v7, v4, vcc
	v_cmp_lt_f32_e64 vcc, |v3|, s7
	s_nop 1
	v_cndmask_b32_e32 v3, v4, v3, vcc
	v_mul_f32_e32 v90, 0xbfb8aa3b, v3
	v_ldexp_f32 v3, v5, v10
	v_cmp_nlt_f32_e32 vcc, s10, v6
	s_movk_i32 s10, 0x1400
	v_exp_f32_e64 v95, -v90
	v_cndmask_b32_e32 v3, 0, v3, vcc
	v_cmp_ngt_f32_e32 vcc, s11, v6
	s_nop 1
	v_cndmask_b32_e32 v3, v7, v3, vcc
	v_add_f32_e32 v6, 1.0, v3
	v_add_f32_e32 v4, -1.0, v6
	v_sub_f32_e32 v5, v4, v6
	v_add_f32_e32 v5, 1.0, v5
	v_sub_f32_e32 v4, v3, v4
	v_add_f32_e32 v10, v4, v5
	v_frexp_mant_f32_e32 v11, v6
	v_cvt_f64_f32_e32 v[4:5], v6
	v_frexp_exp_i32_f64_e32 v4, v[4:5]
	v_cmp_gt_f32_e32 vcc, s12, v11
	s_nop 1
	v_subbrev_co_u32_e32 v4, vcc, 0, v4, vcc
	v_sub_u32_e32 v5, 0, v4
	v_ldexp_f32 v6, v6, v5
	v_ldexp_f32 v5, v10, v5
	v_add_f32_e32 v10, -1.0, v6
	v_add_f32_e32 v13, 1.0, v6
	v_add_f32_e32 v11, 1.0, v10
	v_add_f32_e32 v14, -1.0, v13
	v_sub_f32_e32 v11, v6, v11
	v_sub_f32_e32 v6, v6, v14
	v_add_f32_e32 v11, v5, v11
	v_add_f32_e32 v5, v5, v6
	v_add_f32_e32 v6, v13, v5
	v_rcp_f32_e32 v14, v6
	v_add_f32_e32 v12, v10, v11
	v_sub_f32_e32 v10, v10, v12
	v_add_f32_e32 v10, v11, v10
	v_sub_f32_e32 v11, v13, v6
	v_add_f32_e32 v5, v5, v11
	v_mul_f32_e32 v11, v12, v14
	v_mul_f32_e32 v13, v6, v11
	v_fma_f32 v15, v11, v6, -v13
	v_fmac_f32_e32 v15, v11, v5
	v_add_f32_e32 v16, v13, v15
	v_sub_f32_e32 v17, v12, v16
	v_sub_f32_e32 v12, v12, v17
	v_sub_f32_e32 v13, v16, v13
	v_sub_f32_e32 v12, v12, v16
	v_add_f32_e32 v10, v10, v12
	v_sub_f32_e32 v12, v13, v15
	v_add_f32_e32 v10, v12, v10
	v_add_f32_e32 v12, v17, v10
	v_mul_f32_e32 v13, v14, v12
	v_mul_f32_e32 v15, v6, v13
	v_fma_f32 v6, v13, v6, -v15
	v_fmac_f32_e32 v6, v13, v5
	v_sub_f32_e32 v5, v17, v12
	v_add_f32_e32 v5, v10, v5
	v_add_f32_e32 v10, v15, v6
	v_sub_f32_e32 v16, v12, v10
	v_sub_f32_e32 v12, v12, v16
	v_sub_f32_e32 v15, v10, v15
	v_sub_f32_e32 v10, v12, v10
	v_add_f32_e32 v5, v5, v10
	v_sub_f32_e32 v6, v15, v6
	v_add_f32_e32 v5, v6, v5
	v_add_f32_e32 v6, v11, v13
	v_add_f32_e32 v5, v16, v5
	v_sub_f32_e32 v10, v6, v11
	v_mul_f32_e32 v5, v14, v5
	v_sub_f32_e32 v10, v13, v10
	v_add_f32_e32 v5, v10, v5
	v_cvt_f32_i32_e32 v4, v4
	v_add_f32_e32 v10, v6, v5
	v_mul_f32_e32 v11, v10, v10
	v_fmac_f32_e32 v8, 0x3e9b6dac, v11
	v_fmac_f32_e32 v9, v11, v8
	v_mul_f32_e32 v8, 0x3f317218, v4
	v_fma_f32 v12, v4, s8, -v8
	v_fmac_f32_e32 v12, 0xb102e308, v4
	v_sub_f32_e32 v4, v10, v6
	v_sub_f32_e32 v4, v5, v4
	v_add_f32_e32 v5, v8, v12
	v_sub_f32_e32 v6, v5, v8
	v_ldexp_f32 v8, v10, 1
	v_mul_f32_e32 v10, v10, v11
	v_mul_f32_e32 v9, v10, v9
	v_add_f32_e32 v10, v8, v9
	v_sub_f32_e32 v8, v10, v8
	v_ldexp_f32 v4, v4, 1
	v_sub_f32_e32 v8, v9, v8
	v_add_f32_e32 v4, v4, v8
	v_add_f32_e32 v8, v10, v4
	v_sub_f32_e32 v9, v8, v10
	v_sub_f32_e32 v4, v4, v9
	v_add_f32_e32 v9, v5, v8
	v_sub_f32_e32 v10, v9, v5
	v_sub_f32_e32 v11, v9, v10
	v_sub_f32_e32 v6, v12, v6
	v_sub_f32_e32 v5, v5, v11
	v_sub_f32_e32 v8, v8, v10
	v_add_f32_e32 v5, v8, v5
	v_add_f32_e32 v8, v6, v4
	v_sub_f32_e32 v10, v8, v6
	v_sub_f32_e32 v11, v8, v10
	v_sub_f32_e32 v6, v6, v11
	v_sub_f32_e32 v4, v4, v10
	v_add_f32_e32 v5, v8, v5
	v_add_f32_e32 v4, v4, v6
	v_add_f32_e32 v6, v9, v5
	v_sub_f32_e32 v8, v6, v9
	v_sub_f32_e32 v5, v5, v8
	v_add_f32_e32 v4, v4, v5
	v_add_f32_e32 v4, v6, v4
	v_cmp_neq_f32_e32 vcc, s4, v3
	v_lshlrev_b32_e32 v8, 4, v2
	v_and_b32_e32 v8, 0xf0, v8
	v_cndmask_b32_e32 v4, v7, v4, vcc
	v_cmp_lt_f32_e64 vcc, |v3|, s7
	s_mul_i32 s7, s3, 0x1200
	s_lshl_b32 s3, s3, 4
	v_cndmask_b32_e32 v3, v4, v3, vcc
	v_mul_f32_e32 v99, 0xbfb8aa3b, v3
	v_mul_f32_e32 v3, 0x80000000, v90
	v_exp_f32_e32 v97, v3
	v_mul_f32_e32 v3, 0, v99
	v_exp_f32_e32 v98, v3
	v_mul_f32_e32 v3, -2.0, v90
	v_exp_f32_e32 v93, v3
	v_add_f32_e32 v3, v99, v99
	v_exp_f32_e32 v94, v3
	v_mul_f32_e32 v3, 0xc0400000, v90
	v_exp_f32_e32 v91, v3
	v_mul_f32_e32 v3, 0x40400000, v99
	v_exp_f32_e32 v92, v3
	v_or_b32_e32 v3, s0, v18
	v_or_b32_e32 v4, s1, v3
	v_add_u32_e32 v6, s3, v4
	v_mov_b64_e32 v[4:5], s[68:69]
	v_mad_i64_i32 v[6:7], s[8:9], v6, s10, v[4:5]
	v_lshl_add_u64 v[6:7], v[6:7], 0, s[62:63]
	v_lshl_add_u64 v[6:7], v[6:7], 0, v[78:79]
	global_load_dwordx4 v[30:33], v[6:7], off
	global_load_dwordx4 v[22:25], v[6:7], off offset:64
	global_load_dwordx4 v[14:17], v[6:7], off offset:128
	global_load_dwordx4 v[10:13], v[6:7], off offset:192
	v_add_u32_e32 v6, s1, v26
	v_mad_i64_i32 v[6:7], s[8:9], v6, s10, v[4:5]
	v_lshl_add_u64 v[6:7], v[6:7], 0, s[62:63]
	v_mov_b32_e32 v9, v79
	v_lshl_add_u64 v[6:7], v[6:7], 0, v[8:9]
	global_load_dwordx4 v[50:53], v[6:7], off offset:1024
	global_load_dwordx4 v[54:57], v[6:7], off offset:2048
	v_add_u32_e32 v6, 0x200, v2
	v_ashrrev_i32_e32 v6, 4, v6
	v_add_u32_e32 v7, s1, v6
	v_mad_i64_i32 v[4:5], s[8:9], v7, s10, v[4:5]
	v_lshl_add_u64 v[4:5], v[4:5], 0, s[62:63]
	v_lshl_add_u64 v[4:5], v[4:5], 0, v[8:9]
	global_load_dwordx4 v[58:61], v[4:5], off offset:1024
	global_load_dwordx4 v[62:65], v[4:5], off offset:2048
	v_lshlrev_b32_e32 v7, 2, v19
	s_lshl_b32 s4, s5, 7
	s_add_i32 s5, s7, 0
	v_sub_u32_e32 v3, v3, v7
	v_bfe_u32 v2, v2, 2, 2
	v_add_u32_e32 v4, 0, v8
	v_add_u32_e32 v5, 0, v78
	v_add_u32_e32 v101, s3, v3
	v_mov_b32_e32 v3, s5
	v_or_b32_e32 v2, v20, v2
	s_movk_i32 s5, 0x110
	v_mul_u32_u24_e32 v9, 0x110, v2
	v_mad_u64_u32 v[82:83], s[8:9], v26, s5, v[4:5]
	v_mad_u64_u32 v[80:81], s[8:9], v6, s5, v[4:5]
	v_sub_u32_e32 v2, v7, v18
	s_movk_i32 s7, 0x90
	v_subrev_u32_e32 v2, s3, v2
	s_add_u32 s8, s54, s62
	v_mad_u32_u24 v102, v18, s7, v3
	v_and_b32_e32 v3, 24, v21
	v_subrev_u32_e32 v103, s0, v2
	v_add_u32_e32 v2, s6, v6
	s_addc_u32 s9, s55, 0
	v_exp_f32_e32 v96, v99
	v_add_u32_e32 v8, 0, v3
	v_add_u32_e32 v6, 0x840, v2
	v_mov_b64_e32 v[2:3], s[8:9]
	v_mad_i64_i32 v[86:87], s[8:9], v6, s10, v[2:3]
	v_add_u32_e32 v6, s6, v26
	v_mul_u32_u24_e32 v4, 0x110, v18
	v_add_u32_e32 v6, 0x840, v6
	v_add_u32_e32 v100, v102, v20
	v_add_u32_e32 v104, 49, v103
	v_add_u32_e32 v105, 50, v103
	v_add_u32_e32 v106, 51, v103
	v_add_u32_e32 v107, 33, v103
	v_add_u32_e32 v108, 34, v103
	v_add_u32_e32 v109, 35, v103
	v_add_u32_e32 v110, 17, v103
	v_add_u32_e32 v111, 18, v103
	v_add_u32_e32 v112, 19, v103
	v_add_u32_e32 v113, 3, v103
	v_add_u32_e32 v114, 2, v103
	v_add_u32_e32 v115, 1, v103
	v_mad_i64_i32 v[88:89], s[6:7], v6, s10, v[2:3]
	s_mov_b32 s5, 0x6400000
	v_add_u32_e32 v83, v5, v4
	v_add_u32_e32 v81, v8, v9
	s_mov_b32 s62, s63
	v_mov_b32_e32 v26, v79
	v_mov_b32_e32 v18, v79
	v_mov_b32_e32 v19, v79
	v_mov_b32_e32 v20, v79
	v_mov_b32_e32 v21, v79
	v_mov_b32_e32 v2, v79
	v_mov_b32_e32 v3, v79
	v_mov_b32_e32 v4, v79
	v_mov_b32_e32 v5, v79
	v_mov_b32_e32 v6, v79
	v_mov_b32_e32 v7, v79
	v_mov_b32_e32 v8, v79
	v_mov_b32_e32 v9, v79
